# non-temporal hint also on the out (f32 residual stream) stores of both out-projection epilogues
# speedup vs baseline: 1.1090x; 1.0303x over previous
; #define LAS __attribute__((address_space(3)))
;     __device__ __forceinline__ void operator()(const f32x4 (&acc)[2][2][4][2], const Unit& u, int wr, int wc, int fr, int fq, LAS unsigned char*) const {
;         const int row0 = u.pm * BM + wr * 64 + fr; const int col0 = u.pn * BM + wc * 32 + 8 * fq;
; #pragma unroll
;         for (int ai = 0; ai < 2; ++ai)
; #pragma unroll
;             for (int m = 0; m < 4; ++m) { const size_t ro = (size_t)(row0 + ai * HALF + m * 16) * ldc + col0;
; #pragma unroll
;                 for (int bj = 0; bj < 2; ++bj) { const size_t o = ro + bj * HALF; const f32x4 r0 = *(const f32x4*)(res + o), r1 = *(const f32x4*)(res + o + 4);
;                     *(f32x4*)(O + o) = r0 + acc[ai][bj][m][0]; *(f32x4*)(O + o + 4) = r1 + acc[ai][bj][m][1]; } }
.LBB0_762:
	v_and_b32_e32 v176, 8, v140
	v_sub_u32_e32 v166, v140, v176
	v_lshl_add_u32 v166, s39, 8, v166
	v_mov_b32_e32 v167, 0
	v_lshlrev_b64 v[138:139], 12, v[166:167]
	v_lshl_add_u64 v[138:139], s[76:77], 0, v[138:139]
	v_lshl_or_b32 v166, s5, 8, v142
	v_lshlrev_b32_e32 v166, 2, v166
	v_lshl_add_u32 v166, v176, 1, v166
	v_lshl_add_u64 v[138:139], v[138:139], 0, v[166:167]
	s_mov_b64 s[16:17], 0x8000
	s_mov_b64 s[18:19], 0x10000
	s_mov_b64 s[40:41], 0x50000
	v_lshl_add_u64 v[160:161], v[138:139], 0, s[16:17]
	v_mov_b64_e32 v[162:163], v[138:139]
	v_mov_b64_e32 v[164:165], v[160:161]
	global_load_dwordx4 v[196:199], v[138:139], off nt
	global_load_dwordx4 v[200:203], v[138:139], off offset:512 nt
	global_load_dwordx4 v[204:207], v[160:161], off nt
	global_load_dwordx4 v[208:211], v[160:161], off offset:512 nt
	v_lshl_add_u64 v[138:139], v[138:139], 0, s[18:19]
	v_lshl_add_u64 v[160:161], v[160:161], 0, s[18:19]
	global_load_dwordx4 v[212:215], v[138:139], off nt
	global_load_dwordx4 v[216:219], v[138:139], off offset:512 nt
	global_load_dwordx4 v[220:223], v[160:161], off nt
	global_load_dwordx4 v[224:227], v[160:161], off offset:512 nt
	v_lshl_add_u64 v[138:139], v[138:139], 0, s[18:19]
	v_lshl_add_u64 v[160:161], v[160:161], 0, s[18:19]
	global_load_dwordx4 v[228:231], v[138:139], off nt
	global_load_dwordx4 v[232:235], v[138:139], off offset:512 nt
	global_load_dwordx4 v[236:239], v[160:161], off nt
	global_load_dwordx4 v[240:243], v[160:161], off offset:512 nt
	v_lshl_add_u64 v[138:139], v[138:139], 0, s[18:19]
	v_lshl_add_u64 v[160:161], v[160:161], 0, s[18:19]
	global_load_dwordx4 v[168:171], v[138:139], off nt
	global_load_dwordx4 v[172:175], v[138:139], off offset:512 nt
	global_load_dwordx4 v[180:183], v[160:161], off nt
	global_load_dwordx4 v[156:159], v[160:161], off offset:512 nt
	v_lshl_add_u64 v[138:139], v[138:139], 0, s[40:41]
	v_lshl_add_u64 v[160:161], v[160:161], 0, s[40:41]
	v_mov_b32_dpp v176, v124 row_ror:8 row_mask:0xf bank_mask:0xf
	v_mov_b32_dpp v177, v125 row_ror:8 row_mask:0xf bank_mask:0xf
	v_mov_b32_dpp v124, v120 row_ror:8 row_mask:0xf bank_mask:0xc
	v_mov_b32_dpp v125, v121 row_ror:8 row_mask:0xf bank_mask:0xc
	v_mov_b32_dpp v120, v176 quad_perm:[0,1,2,3] row_mask:0xf bank_mask:0x3
	v_mov_b32_dpp v121, v177 quad_perm:[0,1,2,3] row_mask:0xf bank_mask:0x3
	v_mov_b32_dpp v176, v126 row_ror:8 row_mask:0xf bank_mask:0xf
	v_mov_b32_dpp v177, v127 row_ror:8 row_mask:0xf bank_mask:0xf
	v_mov_b32_dpp v126, v122 row_ror:8 row_mask:0xf bank_mask:0xc
	v_mov_b32_dpp v127, v123 row_ror:8 row_mask:0xf bank_mask:0xc
	v_mov_b32_dpp v122, v176 quad_perm:[0,1,2,3] row_mask:0xf bank_mask:0x3
	v_mov_b32_dpp v123, v177 quad_perm:[0,1,2,3] row_mask:0xf bank_mask:0x3
	v_mov_b32_dpp v176, v116 row_ror:8 row_mask:0xf bank_mask:0xf
	v_mov_b32_dpp v177, v117 row_ror:8 row_mask:0xf bank_mask:0xf
	v_mov_b32_dpp v116, v112 row_ror:8 row_mask:0xf bank_mask:0xc
	v_mov_b32_dpp v117, v113 row_ror:8 row_mask:0xf bank_mask:0xc
	v_mov_b32_dpp v112, v176 quad_perm:[0,1,2,3] row_mask:0xf bank_mask:0x3
	v_mov_b32_dpp v113, v177 quad_perm:[0,1,2,3] row_mask:0xf bank_mask:0x3
	v_mov_b32_dpp v176, v118 row_ror:8 row_mask:0xf bank_mask:0xf
	v_mov_b32_dpp v177, v119 row_ror:8 row_mask:0xf bank_mask:0xf
	v_mov_b32_dpp v118, v114 row_ror:8 row_mask:0xf bank_mask:0xc
	v_mov_b32_dpp v119, v115 row_ror:8 row_mask:0xf bank_mask:0xc
	v_mov_b32_dpp v114, v176 quad_perm:[0,1,2,3] row_mask:0xf bank_mask:0x3
	v_mov_b32_dpp v115, v177 quad_perm:[0,1,2,3] row_mask:0xf bank_mask:0x3
	v_mov_b32_dpp v176, v108 row_ror:8 row_mask:0xf bank_mask:0xf
	v_mov_b32_dpp v177, v109 row_ror:8 row_mask:0xf bank_mask:0xf
	v_mov_b32_dpp v108, v104 row_ror:8 row_mask:0xf bank_mask:0xc
	v_mov_b32_dpp v109, v105 row_ror:8 row_mask:0xf bank_mask:0xc
	v_mov_b32_dpp v104, v176 quad_perm:[0,1,2,3] row_mask:0xf bank_mask:0x3
	v_mov_b32_dpp v105, v177 quad_perm:[0,1,2,3] row_mask:0xf bank_mask:0x3
	v_mov_b32_dpp v176, v110 row_ror:8 row_mask:0xf bank_mask:0xf
	v_mov_b32_dpp v177, v111 row_ror:8 row_mask:0xf bank_mask:0xf
	v_mov_b32_dpp v110, v106 row_ror:8 row_mask:0xf bank_mask:0xc
	v_mov_b32_dpp v111, v107 row_ror:8 row_mask:0xf bank_mask:0xc
	v_mov_b32_dpp v106, v176 quad_perm:[0,1,2,3] row_mask:0xf bank_mask:0x3
	v_mov_b32_dpp v107, v177 quad_perm:[0,1,2,3] row_mask:0xf bank_mask:0x3
	v_mov_b32_dpp v176, v92 row_ror:8 row_mask:0xf bank_mask:0xf
	v_mov_b32_dpp v177, v93 row_ror:8 row_mask:0xf bank_mask:0xf
	v_mov_b32_dpp v92, v88 row_ror:8 row_mask:0xf bank_mask:0xc
	v_mov_b32_dpp v93, v89 row_ror:8 row_mask:0xf bank_mask:0xc
	v_mov_b32_dpp v88, v176 quad_perm:[0,1,2,3] row_mask:0xf bank_mask:0x3
	v_mov_b32_dpp v89, v177 quad_perm:[0,1,2,3] row_mask:0xf bank_mask:0x3
	v_mov_b32_dpp v176, v94 row_ror:8 row_mask:0xf bank_mask:0xf
	v_mov_b32_dpp v177, v95 row_ror:8 row_mask:0xf bank_mask:0xf
	v_mov_b32_dpp v94, v90 row_ror:8 row_mask:0xf bank_mask:0xc
	v_mov_b32_dpp v95, v91 row_ror:8 row_mask:0xf bank_mask:0xc
	v_mov_b32_dpp v90, v176 quad_perm:[0,1,2,3] row_mask:0xf bank_mask:0x3
	v_mov_b32_dpp v91, v177 quad_perm:[0,1,2,3] row_mask:0xf bank_mask:0x3
	v_mov_b32_dpp v176, v100 row_ror:8 row_mask:0xf bank_mask:0xf
	v_mov_b32_dpp v177, v101 row_ror:8 row_mask:0xf bank_mask:0xf
	v_mov_b32_dpp v100, v96 row_ror:8 row_mask:0xf bank_mask:0xc
	v_mov_b32_dpp v101, v97 row_ror:8 row_mask:0xf bank_mask:0xc
	v_mov_b32_dpp v96, v176 quad_perm:[0,1,2,3] row_mask:0xf bank_mask:0x3
	v_mov_b32_dpp v97, v177 quad_perm:[0,1,2,3] row_mask:0xf bank_mask:0x3
	v_mov_b32_dpp v176, v102 row_ror:8 row_mask:0xf bank_mask:0xf
	v_mov_b32_dpp v177, v103 row_ror:8 row_mask:0xf bank_mask:0xf
; #define LAS __attribute__((address_space(3)))
;     __device__ __forceinline__ void operator()(const f32x4 (&acc)[2][2][4][2], const Unit& u, int wr, int wc, int fr, int fq, LAS unsigned char*) const {
;         const int row0 = u.pm * BM + wr * 64 + fr; const int col0 = u.pn * BM + wc * 32 + 8 * fq;
; #pragma unroll
;         for (int ai = 0; ai < 2; ++ai)
; #pragma unroll
;             for (int m = 0; m < 4; ++m) { const size_t ro = (size_t)(row0 + ai * HALF + m * 16) * ldc + col0;
; #pragma unroll
;                 for (int bj = 0; bj < 2; ++bj) { const size_t o = ro + bj * HALF; const f32x4 r0 = *(const f32x4*)(res + o), r1 = *(const f32x4*)(res + o + 4);
;                     *(f32x4*)(O + o) = r0 + acc[ai][bj][m][0]; *(f32x4*)(O + o + 4) = r1 + acc[ai][bj][m][1]; } }
	v_mov_b32_dpp v102, v98 row_ror:8 row_mask:0xf bank_mask:0xc
	v_mov_b32_dpp v103, v99 row_ror:8 row_mask:0xf bank_mask:0xc
	v_mov_b32_dpp v98, v176 quad_perm:[0,1,2,3] row_mask:0xf bank_mask:0x3
	v_mov_b32_dpp v99, v177 quad_perm:[0,1,2,3] row_mask:0xf bank_mask:0x3
	v_mov_b32_dpp v176, v76 row_ror:8 row_mask:0xf bank_mask:0xf
	v_mov_b32_dpp v177, v77 row_ror:8 row_mask:0xf bank_mask:0xf
	v_mov_b32_dpp v76, v72 row_ror:8 row_mask:0xf bank_mask:0xc
	v_mov_b32_dpp v77, v73 row_ror:8 row_mask:0xf bank_mask:0xc
	v_mov_b32_dpp v72, v176 quad_perm:[0,1,2,3] row_mask:0xf bank_mask:0x3
	v_mov_b32_dpp v73, v177 quad_perm:[0,1,2,3] row_mask:0xf bank_mask:0x3
	v_mov_b32_dpp v176, v78 row_ror:8 row_mask:0xf bank_mask:0xf
	v_mov_b32_dpp v177, v79 row_ror:8 row_mask:0xf bank_mask:0xf
	v_mov_b32_dpp v78, v74 row_ror:8 row_mask:0xf bank_mask:0xc
	v_mov_b32_dpp v79, v75 row_ror:8 row_mask:0xf bank_mask:0xc
	v_mov_b32_dpp v74, v176 quad_perm:[0,1,2,3] row_mask:0xf bank_mask:0x3
	v_mov_b32_dpp v75, v177 quad_perm:[0,1,2,3] row_mask:0xf bank_mask:0x3
	v_mov_b32_dpp v176, v84 row_ror:8 row_mask:0xf bank_mask:0xf
	v_mov_b32_dpp v177, v85 row_ror:8 row_mask:0xf bank_mask:0xf
	v_mov_b32_dpp v84, v80 row_ror:8 row_mask:0xf bank_mask:0xc
	v_mov_b32_dpp v85, v81 row_ror:8 row_mask:0xf bank_mask:0xc
	v_mov_b32_dpp v80, v176 quad_perm:[0,1,2,3] row_mask:0xf bank_mask:0x3
	v_mov_b32_dpp v81, v177 quad_perm:[0,1,2,3] row_mask:0xf bank_mask:0x3
	v_mov_b32_dpp v176, v86 row_ror:8 row_mask:0xf bank_mask:0xf
	v_mov_b32_dpp v177, v87 row_ror:8 row_mask:0xf bank_mask:0xf
	v_mov_b32_dpp v86, v82 row_ror:8 row_mask:0xf bank_mask:0xc
	v_mov_b32_dpp v87, v83 row_ror:8 row_mask:0xf bank_mask:0xc
	v_mov_b32_dpp v82, v176 quad_perm:[0,1,2,3] row_mask:0xf bank_mask:0x3
	v_mov_b32_dpp v83, v177 quad_perm:[0,1,2,3] row_mask:0xf bank_mask:0x3
	v_mov_b32_dpp v176, v68 row_ror:8 row_mask:0xf bank_mask:0xf
	v_mov_b32_dpp v177, v69 row_ror:8 row_mask:0xf bank_mask:0xf
	v_mov_b32_dpp v68, v64 row_ror:8 row_mask:0xf bank_mask:0xc
	v_mov_b32_dpp v69, v65 row_ror:8 row_mask:0xf bank_mask:0xc
	v_mov_b32_dpp v64, v176 quad_perm:[0,1,2,3] row_mask:0xf bank_mask:0x3
	v_mov_b32_dpp v65, v177 quad_perm:[0,1,2,3] row_mask:0xf bank_mask:0x3
	v_mov_b32_dpp v176, v70 row_ror:8 row_mask:0xf bank_mask:0xf
	v_mov_b32_dpp v177, v71 row_ror:8 row_mask:0xf bank_mask:0xf
	v_mov_b32_dpp v70, v66 row_ror:8 row_mask:0xf bank_mask:0xc
	v_mov_b32_dpp v71, v67 row_ror:8 row_mask:0xf bank_mask:0xc
	v_mov_b32_dpp v66, v176 quad_perm:[0,1,2,3] row_mask:0xf bank_mask:0x3
	v_mov_b32_dpp v67, v177 quad_perm:[0,1,2,3] row_mask:0xf bank_mask:0x3
	v_mov_b32_dpp v176, v60 row_ror:8 row_mask:0xf bank_mask:0xf
	v_mov_b32_dpp v177, v61 row_ror:8 row_mask:0xf bank_mask:0xf
	v_mov_b32_dpp v60, v56 row_ror:8 row_mask:0xf bank_mask:0xc
	v_mov_b32_dpp v61, v57 row_ror:8 row_mask:0xf bank_mask:0xc
	v_mov_b32_dpp v56, v176 quad_perm:[0,1,2,3] row_mask:0xf bank_mask:0x3
	v_mov_b32_dpp v57, v177 quad_perm:[0,1,2,3] row_mask:0xf bank_mask:0x3
	v_mov_b32_dpp v176, v62 row_ror:8 row_mask:0xf bank_mask:0xf
	v_mov_b32_dpp v177, v63 row_ror:8 row_mask:0xf bank_mask:0xf
	v_mov_b32_dpp v62, v58 row_ror:8 row_mask:0xf bank_mask:0xc
	v_mov_b32_dpp v63, v59 row_ror:8 row_mask:0xf bank_mask:0xc
	v_mov_b32_dpp v58, v176 quad_perm:[0,1,2,3] row_mask:0xf bank_mask:0x3
	v_mov_b32_dpp v59, v177 quad_perm:[0,1,2,3] row_mask:0xf bank_mask:0x3
	v_mov_b32_dpp v176, v52 row_ror:8 row_mask:0xf bank_mask:0xf
	v_mov_b32_dpp v177, v53 row_ror:8 row_mask:0xf bank_mask:0xf
	v_mov_b32_dpp v52, v48 row_ror:8 row_mask:0xf bank_mask:0xc
	v_mov_b32_dpp v53, v49 row_ror:8 row_mask:0xf bank_mask:0xc
	v_mov_b32_dpp v48, v176 quad_perm:[0,1,2,3] row_mask:0xf bank_mask:0x3
	v_mov_b32_dpp v49, v177 quad_perm:[0,1,2,3] row_mask:0xf bank_mask:0x3
	v_mov_b32_dpp v176, v54 row_ror:8 row_mask:0xf bank_mask:0xf
	v_mov_b32_dpp v177, v55 row_ror:8 row_mask:0xf bank_mask:0xf
	v_mov_b32_dpp v54, v50 row_ror:8 row_mask:0xf bank_mask:0xc
	v_mov_b32_dpp v55, v51 row_ror:8 row_mask:0xf bank_mask:0xc
	v_mov_b32_dpp v50, v176 quad_perm:[0,1,2,3] row_mask:0xf bank_mask:0x3
	v_mov_b32_dpp v51, v177 quad_perm:[0,1,2,3] row_mask:0xf bank_mask:0x3
	v_mov_b32_dpp v176, v44 row_ror:8 row_mask:0xf bank_mask:0xf
	v_mov_b32_dpp v177, v45 row_ror:8 row_mask:0xf bank_mask:0xf
	v_mov_b32_dpp v44, v40 row_ror:8 row_mask:0xf bank_mask:0xc
	v_mov_b32_dpp v45, v41 row_ror:8 row_mask:0xf bank_mask:0xc
	v_mov_b32_dpp v40, v176 quad_perm:[0,1,2,3] row_mask:0xf bank_mask:0x3
	v_mov_b32_dpp v41, v177 quad_perm:[0,1,2,3] row_mask:0xf bank_mask:0x3
	v_mov_b32_dpp v176, v46 row_ror:8 row_mask:0xf bank_mask:0xf
	v_mov_b32_dpp v177, v47 row_ror:8 row_mask:0xf bank_mask:0xf
	v_mov_b32_dpp v46, v42 row_ror:8 row_mask:0xf bank_mask:0xc
	v_mov_b32_dpp v47, v43 row_ror:8 row_mask:0xf bank_mask:0xc
	v_mov_b32_dpp v42, v176 quad_perm:[0,1,2,3] row_mask:0xf bank_mask:0x3
	v_mov_b32_dpp v43, v177 quad_perm:[0,1,2,3] row_mask:0xf bank_mask:0x3
	v_mov_b32_dpp v176, v36 row_ror:8 row_mask:0xf bank_mask:0xf
	v_mov_b32_dpp v177, v37 row_ror:8 row_mask:0xf bank_mask:0xf
	v_mov_b32_dpp v36, v32 row_ror:8 row_mask:0xf bank_mask:0xc
	v_mov_b32_dpp v37, v33 row_ror:8 row_mask:0xf bank_mask:0xc
	v_mov_b32_dpp v32, v176 quad_perm:[0,1,2,3] row_mask:0xf bank_mask:0x3
	v_mov_b32_dpp v33, v177 quad_perm:[0,1,2,3] row_mask:0xf bank_mask:0x3
	v_mov_b32_dpp v176, v38 row_ror:8 row_mask:0xf bank_mask:0xf
	v_mov_b32_dpp v177, v39 row_ror:8 row_mask:0xf bank_mask:0xf
	v_mov_b32_dpp v38, v34 row_ror:8 row_mask:0xf bank_mask:0xc
	v_mov_b32_dpp v39, v35 row_ror:8 row_mask:0xf bank_mask:0xc
	v_mov_b32_dpp v34, v176 quad_perm:[0,1,2,3] row_mask:0xf bank_mask:0x3
;     __device__ __forceinline__ void operator()(const f32x4 (&acc)[2][2][4][2], const Unit& u, int wr, int wc, int fr, int fq, LAS unsigned char*) const {
;     ...
;             for (int m = 0; m < 4; ++m) { const size_t ro = (size_t)(row0 + ai * HALF + m * 16) * ldc + col0;
; #pragma unroll
;                 for (int bj = 0; bj < 2; ++bj) { const size_t o = ro + bj * HALF; const f32x4 r0 = *(const f32x4*)(res + o), r1 = *(const f32x4*)(res + o + 4);
;                     *(f32x4*)(O + o) = r0 + acc[ai][bj][m][0]; *(f32x4*)(O + o + 4) = r1 + acc[ai][bj][m][1]; } }
	v_mov_b32_dpp v35, v177 quad_perm:[0,1,2,3] row_mask:0xf bank_mask:0x3
	v_mov_b32_dpp v176, v28 row_ror:8 row_mask:0xf bank_mask:0xf
	v_mov_b32_dpp v177, v29 row_ror:8 row_mask:0xf bank_mask:0xf
	v_mov_b32_dpp v28, v24 row_ror:8 row_mask:0xf bank_mask:0xc
	v_mov_b32_dpp v29, v25 row_ror:8 row_mask:0xf bank_mask:0xc
	v_mov_b32_dpp v24, v176 quad_perm:[0,1,2,3] row_mask:0xf bank_mask:0x3
	v_mov_b32_dpp v25, v177 quad_perm:[0,1,2,3] row_mask:0xf bank_mask:0x3
	v_mov_b32_dpp v176, v30 row_ror:8 row_mask:0xf bank_mask:0xf
	v_mov_b32_dpp v177, v31 row_ror:8 row_mask:0xf bank_mask:0xf
	v_mov_b32_dpp v30, v26 row_ror:8 row_mask:0xf bank_mask:0xc
	v_mov_b32_dpp v31, v27 row_ror:8 row_mask:0xf bank_mask:0xc
	v_mov_b32_dpp v26, v176 quad_perm:[0,1,2,3] row_mask:0xf bank_mask:0x3
	v_mov_b32_dpp v27, v177 quad_perm:[0,1,2,3] row_mask:0xf bank_mask:0x3
	v_mov_b32_dpp v176, v20 row_ror:8 row_mask:0xf bank_mask:0xf
	v_mov_b32_dpp v177, v21 row_ror:8 row_mask:0xf bank_mask:0xf
	v_mov_b32_dpp v20, v16 row_ror:8 row_mask:0xf bank_mask:0xc
	v_mov_b32_dpp v21, v17 row_ror:8 row_mask:0xf bank_mask:0xc
	v_mov_b32_dpp v16, v176 quad_perm:[0,1,2,3] row_mask:0xf bank_mask:0x3
	v_mov_b32_dpp v17, v177 quad_perm:[0,1,2,3] row_mask:0xf bank_mask:0x3
	v_mov_b32_dpp v176, v22 row_ror:8 row_mask:0xf bank_mask:0xf
	v_mov_b32_dpp v177, v23 row_ror:8 row_mask:0xf bank_mask:0xf
	v_mov_b32_dpp v22, v18 row_ror:8 row_mask:0xf bank_mask:0xc
	v_mov_b32_dpp v23, v19 row_ror:8 row_mask:0xf bank_mask:0xc
	v_mov_b32_dpp v18, v176 quad_perm:[0,1,2,3] row_mask:0xf bank_mask:0x3
	v_mov_b32_dpp v19, v177 quad_perm:[0,1,2,3] row_mask:0xf bank_mask:0x3
	v_mov_b32_dpp v176, v12 row_ror:8 row_mask:0xf bank_mask:0xf
	v_mov_b32_dpp v177, v13 row_ror:8 row_mask:0xf bank_mask:0xf
	v_mov_b32_dpp v12, v8 row_ror:8 row_mask:0xf bank_mask:0xc
	v_mov_b32_dpp v13, v9 row_ror:8 row_mask:0xf bank_mask:0xc
	v_mov_b32_dpp v8, v176 quad_perm:[0,1,2,3] row_mask:0xf bank_mask:0x3
	v_mov_b32_dpp v9, v177 quad_perm:[0,1,2,3] row_mask:0xf bank_mask:0x3
	v_mov_b32_dpp v176, v14 row_ror:8 row_mask:0xf bank_mask:0xf
	v_mov_b32_dpp v177, v15 row_ror:8 row_mask:0xf bank_mask:0xf
	v_mov_b32_dpp v14, v10 row_ror:8 row_mask:0xf bank_mask:0xc
	v_mov_b32_dpp v15, v11 row_ror:8 row_mask:0xf bank_mask:0xc
	v_mov_b32_dpp v10, v176 quad_perm:[0,1,2,3] row_mask:0xf bank_mask:0x3
	v_mov_b32_dpp v11, v177 quad_perm:[0,1,2,3] row_mask:0xf bank_mask:0x3
	v_mov_b32_dpp v176, v4 row_ror:8 row_mask:0xf bank_mask:0xf
	v_mov_b32_dpp v177, v5 row_ror:8 row_mask:0xf bank_mask:0xf
	v_mov_b32_dpp v4, v0 row_ror:8 row_mask:0xf bank_mask:0xc
	v_mov_b32_dpp v5, v1 row_ror:8 row_mask:0xf bank_mask:0xc
	v_mov_b32_dpp v0, v176 quad_perm:[0,1,2,3] row_mask:0xf bank_mask:0x3
	v_mov_b32_dpp v1, v177 quad_perm:[0,1,2,3] row_mask:0xf bank_mask:0x3
	v_mov_b32_dpp v176, v6 row_ror:8 row_mask:0xf bank_mask:0xf
	v_mov_b32_dpp v177, v7 row_ror:8 row_mask:0xf bank_mask:0xf
	v_mov_b32_dpp v6, v2 row_ror:8 row_mask:0xf bank_mask:0xc
	v_mov_b32_dpp v7, v3 row_ror:8 row_mask:0xf bank_mask:0xc
	v_mov_b32_dpp v2, v176 quad_perm:[0,1,2,3] row_mask:0xf bank_mask:0x3
	v_mov_b32_dpp v3, v177 quad_perm:[0,1,2,3] row_mask:0xf bank_mask:0x3
	s_waitcnt vmcnt(12)
	v_pk_add_f32 v[124:125], v[124:125], v[196:197]
	v_pk_add_f32 v[126:127], v[126:127], v[198:199]
	v_pk_add_f32 v[120:121], v[120:121], v[204:205]
	v_pk_add_f32 v[122:123], v[122:123], v[206:207]
	v_pk_add_f32 v[116:117], v[116:117], v[200:201]
	v_pk_add_f32 v[118:119], v[118:119], v[202:203]
	v_pk_add_f32 v[112:113], v[112:113], v[208:209]
	v_pk_add_f32 v[114:115], v[114:115], v[210:211]
	global_store_dwordx4 v[162:163], v[124:127], off nt
	global_store_dwordx4 v[162:163], v[116:119], off offset:512 nt
	global_store_dwordx4 v[164:165], v[120:123], off nt
	global_store_dwordx4 v[164:165], v[112:115], off offset:512 nt
	global_load_dwordx4 v[196:199], v[138:139], off nt
	global_load_dwordx4 v[200:203], v[138:139], off offset:512 nt
	global_load_dwordx4 v[204:207], v[160:161], off nt
	global_load_dwordx4 v[208:211], v[160:161], off offset:512 nt
	v_lshl_add_u64 v[138:139], v[138:139], 0, s[18:19]
	v_lshl_add_u64 v[160:161], v[160:161], 0, s[18:19]
	v_lshl_add_u64 v[162:163], v[162:163], 0, s[18:19]
	v_lshl_add_u64 v[164:165], v[164:165], 0, s[18:19]
	s_waitcnt vmcnt(16)
	v_pk_add_f32 v[108:109], v[108:109], v[212:213]
	v_pk_add_f32 v[110:111], v[110:111], v[214:215]
	v_pk_add_f32 v[104:105], v[104:105], v[220:221]
	v_pk_add_f32 v[106:107], v[106:107], v[222:223]
	v_pk_add_f32 v[92:93], v[92:93], v[216:217]
	v_pk_add_f32 v[94:95], v[94:95], v[218:219]
	v_pk_add_f32 v[88:89], v[88:89], v[224:225]
	v_pk_add_f32 v[90:91], v[90:91], v[226:227]
	global_store_dwordx4 v[162:163], v[108:111], off nt
	global_store_dwordx4 v[162:163], v[92:95], off offset:512 nt
	global_store_dwordx4 v[164:165], v[104:107], off nt
	global_store_dwordx4 v[164:165], v[88:91], off offset:512 nt
	global_load_dwordx4 v[212:215], v[138:139], off nt
	global_load_dwordx4 v[216:219], v[138:139], off offset:512 nt
	global_load_dwordx4 v[220:223], v[160:161], off nt
	global_load_dwordx4 v[224:227], v[160:161], off offset:512 nt
	v_lshl_add_u64 v[138:139], v[138:139], 0, s[18:19]
	v_lshl_add_u64 v[160:161], v[160:161], 0, s[18:19]
	v_lshl_add_u64 v[162:163], v[162:163], 0, s[18:19]
	v_lshl_add_u64 v[164:165], v[164:165], 0, s[18:19]
	s_waitcnt vmcnt(20)
;     __device__ __forceinline__ void operator()(const f32x4 (&acc)[2][2][4][2], const Unit& u, int wr, int wc, int fr, int fq, LAS unsigned char*) const {
;     ...
;             for (int m = 0; m < 4; ++m) { const size_t ro = (size_t)(row0 + ai * HALF + m * 16) * ldc + col0;
; #pragma unroll
;                 for (int bj = 0; bj < 2; ++bj) { const size_t o = ro + bj * HALF; const f32x4 r0 = *(const f32x4*)(res + o), r1 = *(const f32x4*)(res + o + 4);
;                     *(f32x4*)(O + o) = r0 + acc[ai][bj][m][0]; *(f32x4*)(O + o + 4) = r1 + acc[ai][bj][m][1]; } }
	v_pk_add_f32 v[100:101], v[100:101], v[228:229]
	v_pk_add_f32 v[102:103], v[102:103], v[230:231]
	v_pk_add_f32 v[96:97], v[96:97], v[236:237]
	v_pk_add_f32 v[98:99], v[98:99], v[238:239]
	v_pk_add_f32 v[76:77], v[76:77], v[232:233]
	v_pk_add_f32 v[78:79], v[78:79], v[234:235]
	v_pk_add_f32 v[72:73], v[72:73], v[240:241]
	v_pk_add_f32 v[74:75], v[74:75], v[242:243]
	global_store_dwordx4 v[162:163], v[100:103], off nt
	global_store_dwordx4 v[162:163], v[76:79], off offset:512 nt
	global_store_dwordx4 v[164:165], v[96:99], off nt
	global_store_dwordx4 v[164:165], v[72:75], off offset:512 nt
	global_load_dwordx4 v[228:231], v[138:139], off nt
	global_load_dwordx4 v[232:235], v[138:139], off offset:512 nt
	global_load_dwordx4 v[236:239], v[160:161], off nt
	global_load_dwordx4 v[240:243], v[160:161], off offset:512 nt
	v_lshl_add_u64 v[138:139], v[138:139], 0, s[18:19]
	v_lshl_add_u64 v[160:161], v[160:161], 0, s[18:19]
	v_lshl_add_u64 v[162:163], v[162:163], 0, s[18:19]
	v_lshl_add_u64 v[164:165], v[164:165], 0, s[18:19]
	s_waitcnt vmcnt(24)
	v_pk_add_f32 v[84:85], v[84:85], v[168:169]
	v_pk_add_f32 v[86:87], v[86:87], v[170:171]
	v_pk_add_f32 v[80:81], v[80:81], v[180:181]
	v_pk_add_f32 v[82:83], v[82:83], v[182:183]
	v_pk_add_f32 v[68:69], v[68:69], v[172:173]
	v_pk_add_f32 v[70:71], v[70:71], v[174:175]
	v_pk_add_f32 v[64:65], v[64:65], v[156:157]
	v_pk_add_f32 v[66:67], v[66:67], v[158:159]
	global_store_dwordx4 v[162:163], v[84:87], off nt
	global_store_dwordx4 v[162:163], v[68:71], off offset:512 nt
	global_store_dwordx4 v[164:165], v[80:83], off nt
	global_store_dwordx4 v[164:165], v[64:67], off offset:512 nt
	global_load_dwordx4 v[168:171], v[138:139], off nt
	global_load_dwordx4 v[172:175], v[138:139], off offset:512 nt
	global_load_dwordx4 v[180:183], v[160:161], off nt
	global_load_dwordx4 v[156:159], v[160:161], off offset:512 nt
	v_lshl_add_u64 v[162:163], v[162:163], 0, s[40:41]
	v_lshl_add_u64 v[164:165], v[164:165], 0, s[40:41]
	s_waitcnt vmcnt(24)
	v_pk_add_f32 v[60:61], v[60:61], v[196:197]
	v_pk_add_f32 v[62:63], v[62:63], v[198:199]
	v_pk_add_f32 v[56:57], v[56:57], v[204:205]
	v_pk_add_f32 v[58:59], v[58:59], v[206:207]
	v_pk_add_f32 v[52:53], v[52:53], v[200:201]
	v_pk_add_f32 v[54:55], v[54:55], v[202:203]
	v_pk_add_f32 v[48:49], v[48:49], v[208:209]
	v_pk_add_f32 v[50:51], v[50:51], v[210:211]
	global_store_dwordx4 v[162:163], v[60:63], off nt
	global_store_dwordx4 v[162:163], v[52:55], off offset:512 nt
	global_store_dwordx4 v[164:165], v[56:59], off nt
	global_store_dwordx4 v[164:165], v[48:51], off offset:512 nt
	v_lshl_add_u64 v[162:163], v[162:163], 0, s[18:19]
	v_lshl_add_u64 v[164:165], v[164:165], 0, s[18:19]
	s_waitcnt vmcnt(20)
	v_pk_add_f32 v[44:45], v[44:45], v[212:213]
	v_pk_add_f32 v[46:47], v[46:47], v[214:215]
	v_pk_add_f32 v[40:41], v[40:41], v[220:221]
	v_pk_add_f32 v[42:43], v[42:43], v[222:223]
	v_pk_add_f32 v[36:37], v[36:37], v[216:217]
	v_pk_add_f32 v[38:39], v[38:39], v[218:219]
	v_pk_add_f32 v[32:33], v[32:33], v[224:225]
	v_pk_add_f32 v[34:35], v[34:35], v[226:227]
	global_store_dwordx4 v[162:163], v[44:47], off nt
	global_store_dwordx4 v[162:163], v[36:39], off offset:512 nt
	global_store_dwordx4 v[164:165], v[40:43], off nt
	global_store_dwordx4 v[164:165], v[32:35], off offset:512 nt
	v_lshl_add_u64 v[162:163], v[162:163], 0, s[18:19]
	v_lshl_add_u64 v[164:165], v[164:165], 0, s[18:19]
	s_waitcnt vmcnt(16)
	v_pk_add_f32 v[28:29], v[28:29], v[228:229]
	v_pk_add_f32 v[30:31], v[30:31], v[230:231]
	v_pk_add_f32 v[24:25], v[24:25], v[236:237]
	v_pk_add_f32 v[26:27], v[26:27], v[238:239]
	v_pk_add_f32 v[20:21], v[20:21], v[232:233]
	v_pk_add_f32 v[22:23], v[22:23], v[234:235]
	v_pk_add_f32 v[16:17], v[16:17], v[240:241]
	v_pk_add_f32 v[18:19], v[18:19], v[242:243]
	global_store_dwordx4 v[162:163], v[28:31], off nt
	global_store_dwordx4 v[162:163], v[20:23], off offset:512 nt
	global_store_dwordx4 v[164:165], v[24:27], off nt
	global_store_dwordx4 v[164:165], v[16:19], off offset:512 nt
	v_lshl_add_u64 v[162:163], v[162:163], 0, s[18:19]
	v_lshl_add_u64 v[164:165], v[164:165], 0, s[18:19]
	s_waitcnt vmcnt(12)
	v_pk_add_f32 v[12:13], v[12:13], v[168:169]
	v_pk_add_f32 v[14:15], v[14:15], v[170:171]
	v_pk_add_f32 v[8:9], v[8:9], v[180:181]
	v_pk_add_f32 v[10:11], v[10:11], v[182:183]
	v_pk_add_f32 v[4:5], v[4:5], v[172:173]
	v_pk_add_f32 v[6:7], v[6:7], v[174:175]
	v_pk_add_f32 v[0:1], v[0:1], v[156:157]
	v_pk_add_f32 v[2:3], v[2:3], v[158:159]
	global_store_dwordx4 v[162:163], v[12:15], off nt
	global_store_dwordx4 v[162:163], v[4:7], off offset:512 nt
	global_store_dwordx4 v[164:165], v[8:11], off nt
	global_store_dwordx4 v[164:165], v[0:3], off offset:512 nt
	s_mov_b64 s[14:15], -1
	s_and_b64 vcc, exec, s[44:45]
	s_cbranch_vccnz .LBB0_749
	s_andn2_b64 vcc, exec, s[52:53]
	s_cbranch_vccnz .LBB0_748
	s_barrier
	s_branch .LBB0_748

; #define LAS __attribute__((address_space(3)))
;     __device__ __forceinline__ void operator()(const f32x4 (&acc)[2][2][4][2], const Unit& u, int wr, int wc, int fr, int fq, LAS unsigned char* lds) const {
;         const int row0 = u.pm * BM + wr * 64 + fr; const int col0 = u.pn * BM + wc * 32 + 8 * fq;
;         LAS float* part = (LAS float*)(lds + 131072);
;         f32x4 gg[2][2];
; #pragma unroll
;         for (int bj = 0; bj < 2; ++bj)
; #pragma unroll
;             for (int n = 0; n < 2; ++n) gg[bj][n] = *(const f32x4*)(g + col0 + bj * HALF + 4 * n);
; #pragma unroll
;         for (int ai = 0; ai < 2; ++ai)
; #pragma unroll
;             for (int m = 0; m < 4; ++m) { const size_t ro = (size_t)(row0 + ai * HALF + m * 16) * ldc + col0; float ssq = 0.f;
; #pragma unroll
;                 for (int bj = 0; bj < 2; ++bj) { const size_t o = ro + bj * HALF;
;                     const f32x4 r0 = *(const f32x4*)(res + o), r1 = *(const f32x4*)(res + o + 4);
.LBB0_786:
	s_lshl_b32 s46, s4, 8
	v_readlane_b32 s4, v244, 0
	v_readlane_b32 s5, v244, 1
	v_and_b32_e32 v25, 8, v172
	v_sub_u32_e32 v26, v172, v25
	v_add_u32_e32 v26, s46, v26
	v_lshl_or_b32 v27, s56, 8, v174
	v_lshrrev_b32_e32 v25, 1, v25
	v_add_u32_e32 v27, v27, v25
	v_lshl_add_u32 v28, v26, 10, v27
	v_lshlrev_b32_e32 v170, 2, v28
	v_lshlrev_b32_e32 v247, 1, v28
	v_lshlrev_b32_e32 v27, 2, v27
	v_add_u32_e32 v171, 0x8000, v170
	v_add_u32_e32 v24, 0x4000, v247
	v_mov_b32_e32 v177, v170
	v_mov_b32_e32 v195, v171
	v_lshlrev_b32_e32 v54, 2, v193
	v_lshlrev_b32_e32 v55, 2, v194
	global_load_dwordx4 v[180:183], v27, s[4:5]
	global_load_dwordx4 v[166:169], v27, s[4:5] offset:512
	global_load_dwordx4 v[196:199], v170, s[80:81] nt
	global_load_dwordx4 v[200:203], v170, s[80:81] offset:512 nt
	global_load_dwordx4 v[204:207], v171, s[80:81] nt
	global_load_dwordx4 v[208:211], v171, s[80:81] offset:512 nt
	v_add_u32_e32 v170, 0x10000, v170
	v_add_u32_e32 v171, 0x10000, v171
	global_load_dwordx4 v[212:215], v170, s[80:81] nt
	global_load_dwordx4 v[216:219], v170, s[80:81] offset:512 nt
	global_load_dwordx4 v[220:223], v171, s[80:81] nt
	global_load_dwordx4 v[224:227], v171, s[80:81] offset:512 nt
	v_add_u32_e32 v170, 0x10000, v170
	v_add_u32_e32 v171, 0x10000, v171
	global_load_dwordx4 v[228:231], v170, s[80:81] nt
	global_load_dwordx4 v[232:235], v170, s[80:81] offset:512 nt
	global_load_dwordx4 v[236:239], v171, s[80:81] nt
	global_load_dwordx4 v[240:243], v171, s[80:81] offset:512 nt
	v_add_u32_e32 v170, 0x10000, v170
	v_add_u32_e32 v171, 0x10000, v171
	v_mov_b32_dpp v25, v140 row_ror:8 row_mask:0xf bank_mask:0xf
	v_mov_b32_dpp v26, v141 row_ror:8 row_mask:0xf bank_mask:0xf
	v_mov_b32_dpp v140, v136 row_ror:8 row_mask:0xf bank_mask:0xc
	v_mov_b32_dpp v141, v137 row_ror:8 row_mask:0xf bank_mask:0xc
	v_mov_b32_dpp v136, v25 quad_perm:[0,1,2,3] row_mask:0xf bank_mask:0x3
	v_mov_b32_dpp v137, v26 quad_perm:[0,1,2,3] row_mask:0xf bank_mask:0x3
	v_mov_b32_dpp v25, v142 row_ror:8 row_mask:0xf bank_mask:0xf
	v_mov_b32_dpp v26, v143 row_ror:8 row_mask:0xf bank_mask:0xf
	v_mov_b32_dpp v142, v138 row_ror:8 row_mask:0xf bank_mask:0xc
	v_mov_b32_dpp v143, v139 row_ror:8 row_mask:0xf bank_mask:0xc
	v_mov_b32_dpp v138, v25 quad_perm:[0,1,2,3] row_mask:0xf bank_mask:0x3
	v_mov_b32_dpp v139, v26 quad_perm:[0,1,2,3] row_mask:0xf bank_mask:0x3
	v_mov_b32_dpp v25, v132 row_ror:8 row_mask:0xf bank_mask:0xf
	v_mov_b32_dpp v26, v133 row_ror:8 row_mask:0xf bank_mask:0xf
	v_mov_b32_dpp v132, v128 row_ror:8 row_mask:0xf bank_mask:0xc
	v_mov_b32_dpp v133, v129 row_ror:8 row_mask:0xf bank_mask:0xc
	v_mov_b32_dpp v128, v25 quad_perm:[0,1,2,3] row_mask:0xf bank_mask:0x3
	v_mov_b32_dpp v129, v26 quad_perm:[0,1,2,3] row_mask:0xf bank_mask:0x3
	v_mov_b32_dpp v25, v134 row_ror:8 row_mask:0xf bank_mask:0xf
	v_mov_b32_dpp v26, v135 row_ror:8 row_mask:0xf bank_mask:0xf
	v_mov_b32_dpp v134, v130 row_ror:8 row_mask:0xf bank_mask:0xc
	v_mov_b32_dpp v135, v131 row_ror:8 row_mask:0xf bank_mask:0xc
	v_mov_b32_dpp v130, v25 quad_perm:[0,1,2,3] row_mask:0xf bank_mask:0x3
	v_mov_b32_dpp v131, v26 quad_perm:[0,1,2,3] row_mask:0xf bank_mask:0x3
	v_mov_b32_dpp v25, v124 row_ror:8 row_mask:0xf bank_mask:0xf
	v_mov_b32_dpp v26, v125 row_ror:8 row_mask:0xf bank_mask:0xf
	v_mov_b32_dpp v124, v120 row_ror:8 row_mask:0xf bank_mask:0xc
	v_mov_b32_dpp v125, v121 row_ror:8 row_mask:0xf bank_mask:0xc
	v_mov_b32_dpp v120, v25 quad_perm:[0,1,2,3] row_mask:0xf bank_mask:0x3
	v_mov_b32_dpp v121, v26 quad_perm:[0,1,2,3] row_mask:0xf bank_mask:0x3
	v_mov_b32_dpp v25, v126 row_ror:8 row_mask:0xf bank_mask:0xf
	v_mov_b32_dpp v26, v127 row_ror:8 row_mask:0xf bank_mask:0xf
	v_mov_b32_dpp v126, v122 row_ror:8 row_mask:0xf bank_mask:0xc
	v_mov_b32_dpp v127, v123 row_ror:8 row_mask:0xf bank_mask:0xc
	v_mov_b32_dpp v122, v25 quad_perm:[0,1,2,3] row_mask:0xf bank_mask:0x3
	v_mov_b32_dpp v123, v26 quad_perm:[0,1,2,3] row_mask:0xf bank_mask:0x3
	v_mov_b32_dpp v25, v116 row_ror:8 row_mask:0xf bank_mask:0xf
	v_mov_b32_dpp v26, v117 row_ror:8 row_mask:0xf bank_mask:0xf
	v_mov_b32_dpp v116, v112 row_ror:8 row_mask:0xf bank_mask:0xc
	v_mov_b32_dpp v117, v113 row_ror:8 row_mask:0xf bank_mask:0xc
	v_mov_b32_dpp v112, v25 quad_perm:[0,1,2,3] row_mask:0xf bank_mask:0x3
	v_mov_b32_dpp v113, v26 quad_perm:[0,1,2,3] row_mask:0xf bank_mask:0x3
	v_mov_b32_dpp v25, v118 row_ror:8 row_mask:0xf bank_mask:0xf
	v_mov_b32_dpp v26, v119 row_ror:8 row_mask:0xf bank_mask:0xf
	v_mov_b32_dpp v118, v114 row_ror:8 row_mask:0xf bank_mask:0xc
	v_mov_b32_dpp v119, v115 row_ror:8 row_mask:0xf bank_mask:0xc
	v_mov_b32_dpp v114, v25 quad_perm:[0,1,2,3] row_mask:0xf bank_mask:0x3
	v_mov_b32_dpp v115, v26 quad_perm:[0,1,2,3] row_mask:0xf bank_mask:0x3
	v_mov_b32_dpp v25, v108 row_ror:8 row_mask:0xf bank_mask:0xf
	v_mov_b32_dpp v26, v109 row_ror:8 row_mask:0xf bank_mask:0xf
	v_mov_b32_dpp v108, v104 row_ror:8 row_mask:0xf bank_mask:0xc
	v_mov_b32_dpp v109, v105 row_ror:8 row_mask:0xf bank_mask:0xc
	v_mov_b32_dpp v104, v25 quad_perm:[0,1,2,3] row_mask:0xf bank_mask:0x3
	v_mov_b32_dpp v105, v26 quad_perm:[0,1,2,3] row_mask:0xf bank_mask:0x3
	v_mov_b32_dpp v25, v110 row_ror:8 row_mask:0xf bank_mask:0xf
	v_mov_b32_dpp v26, v111 row_ror:8 row_mask:0xf bank_mask:0xf
	v_mov_b32_dpp v110, v106 row_ror:8 row_mask:0xf bank_mask:0xc
	v_mov_b32_dpp v111, v107 row_ror:8 row_mask:0xf bank_mask:0xc
	v_mov_b32_dpp v106, v25 quad_perm:[0,1,2,3] row_mask:0xf bank_mask:0x3
	v_mov_b32_dpp v107, v26 quad_perm:[0,1,2,3] row_mask:0xf bank_mask:0x3
	v_mov_b32_dpp v25, v100 row_ror:8 row_mask:0xf bank_mask:0xf
	v_mov_b32_dpp v26, v101 row_ror:8 row_mask:0xf bank_mask:0xf
;     __device__ __forceinline__ void operator()(const f32x4 (&acc)[2][2][4][2], const Unit& u, int wr, int wc, int fr, int fq, LAS unsigned char* lds) const {
;     ...
;                     const f32x4 r0 = *(const f32x4*)(res + o), r1 = *(const f32x4*)(res + o + 4);
;                     const f32x4 x0 = r0 + acc[ai][bj][m][0], x1 = r1 + acc[ai][bj][m][1];
;                     *(f32x4*)(O + o) = x0; *(f32x4*)(O + o + 4) = x1;
	v_mov_b32_dpp v100, v96 row_ror:8 row_mask:0xf bank_mask:0xc
	v_mov_b32_dpp v101, v97 row_ror:8 row_mask:0xf bank_mask:0xc
	v_mov_b32_dpp v96, v25 quad_perm:[0,1,2,3] row_mask:0xf bank_mask:0x3
	v_mov_b32_dpp v97, v26 quad_perm:[0,1,2,3] row_mask:0xf bank_mask:0x3
	v_mov_b32_dpp v25, v102 row_ror:8 row_mask:0xf bank_mask:0xf
	v_mov_b32_dpp v26, v103 row_ror:8 row_mask:0xf bank_mask:0xf
	v_mov_b32_dpp v102, v98 row_ror:8 row_mask:0xf bank_mask:0xc
	v_mov_b32_dpp v103, v99 row_ror:8 row_mask:0xf bank_mask:0xc
	v_mov_b32_dpp v98, v25 quad_perm:[0,1,2,3] row_mask:0xf bank_mask:0x3
	v_mov_b32_dpp v99, v26 quad_perm:[0,1,2,3] row_mask:0xf bank_mask:0x3
	v_mov_b32_dpp v25, v92 row_ror:8 row_mask:0xf bank_mask:0xf
	v_mov_b32_dpp v26, v93 row_ror:8 row_mask:0xf bank_mask:0xf
	v_mov_b32_dpp v92, v88 row_ror:8 row_mask:0xf bank_mask:0xc
	v_mov_b32_dpp v93, v89 row_ror:8 row_mask:0xf bank_mask:0xc
	v_mov_b32_dpp v88, v25 quad_perm:[0,1,2,3] row_mask:0xf bank_mask:0x3
	v_mov_b32_dpp v89, v26 quad_perm:[0,1,2,3] row_mask:0xf bank_mask:0x3
	v_mov_b32_dpp v25, v94 row_ror:8 row_mask:0xf bank_mask:0xf
	v_mov_b32_dpp v26, v95 row_ror:8 row_mask:0xf bank_mask:0xf
	v_mov_b32_dpp v94, v90 row_ror:8 row_mask:0xf bank_mask:0xc
	v_mov_b32_dpp v95, v91 row_ror:8 row_mask:0xf bank_mask:0xc
	v_mov_b32_dpp v90, v25 quad_perm:[0,1,2,3] row_mask:0xf bank_mask:0x3
	v_mov_b32_dpp v91, v26 quad_perm:[0,1,2,3] row_mask:0xf bank_mask:0x3
	v_mov_b32_dpp v25, v84 row_ror:8 row_mask:0xf bank_mask:0xf
	v_mov_b32_dpp v26, v85 row_ror:8 row_mask:0xf bank_mask:0xf
	v_mov_b32_dpp v84, v80 row_ror:8 row_mask:0xf bank_mask:0xc
	v_mov_b32_dpp v85, v81 row_ror:8 row_mask:0xf bank_mask:0xc
	v_mov_b32_dpp v80, v25 quad_perm:[0,1,2,3] row_mask:0xf bank_mask:0x3
	v_mov_b32_dpp v81, v26 quad_perm:[0,1,2,3] row_mask:0xf bank_mask:0x3
	v_mov_b32_dpp v25, v86 row_ror:8 row_mask:0xf bank_mask:0xf
	v_mov_b32_dpp v26, v87 row_ror:8 row_mask:0xf bank_mask:0xf
	v_mov_b32_dpp v86, v82 row_ror:8 row_mask:0xf bank_mask:0xc
	v_mov_b32_dpp v87, v83 row_ror:8 row_mask:0xf bank_mask:0xc
	v_mov_b32_dpp v82, v25 quad_perm:[0,1,2,3] row_mask:0xf bank_mask:0x3
	v_mov_b32_dpp v83, v26 quad_perm:[0,1,2,3] row_mask:0xf bank_mask:0x3
	v_mov_b32_dpp v25, v76 row_ror:8 row_mask:0xf bank_mask:0xf
	v_mov_b32_dpp v26, v77 row_ror:8 row_mask:0xf bank_mask:0xf
	v_mov_b32_dpp v76, v72 row_ror:8 row_mask:0xf bank_mask:0xc
	v_mov_b32_dpp v77, v73 row_ror:8 row_mask:0xf bank_mask:0xc
	v_mov_b32_dpp v72, v25 quad_perm:[0,1,2,3] row_mask:0xf bank_mask:0x3
	v_mov_b32_dpp v73, v26 quad_perm:[0,1,2,3] row_mask:0xf bank_mask:0x3
	v_mov_b32_dpp v25, v78 row_ror:8 row_mask:0xf bank_mask:0xf
	v_mov_b32_dpp v26, v79 row_ror:8 row_mask:0xf bank_mask:0xf
	v_mov_b32_dpp v78, v74 row_ror:8 row_mask:0xf bank_mask:0xc
	v_mov_b32_dpp v79, v75 row_ror:8 row_mask:0xf bank_mask:0xc
	v_mov_b32_dpp v74, v25 quad_perm:[0,1,2,3] row_mask:0xf bank_mask:0x3
	v_mov_b32_dpp v75, v26 quad_perm:[0,1,2,3] row_mask:0xf bank_mask:0x3
	v_mov_b32_dpp v25, v68 row_ror:8 row_mask:0xf bank_mask:0xf
	v_mov_b32_dpp v26, v69 row_ror:8 row_mask:0xf bank_mask:0xf
	v_mov_b32_dpp v68, v64 row_ror:8 row_mask:0xf bank_mask:0xc
	v_mov_b32_dpp v69, v65 row_ror:8 row_mask:0xf bank_mask:0xc
	v_mov_b32_dpp v64, v25 quad_perm:[0,1,2,3] row_mask:0xf bank_mask:0x3
	v_mov_b32_dpp v65, v26 quad_perm:[0,1,2,3] row_mask:0xf bank_mask:0x3
	v_mov_b32_dpp v25, v70 row_ror:8 row_mask:0xf bank_mask:0xf
	v_mov_b32_dpp v26, v71 row_ror:8 row_mask:0xf bank_mask:0xf
	v_mov_b32_dpp v70, v66 row_ror:8 row_mask:0xf bank_mask:0xc
	v_mov_b32_dpp v71, v67 row_ror:8 row_mask:0xf bank_mask:0xc
	v_mov_b32_dpp v66, v25 quad_perm:[0,1,2,3] row_mask:0xf bank_mask:0x3
	v_mov_b32_dpp v67, v26 quad_perm:[0,1,2,3] row_mask:0xf bank_mask:0x3
	v_mov_b32_dpp v25, v60 row_ror:8 row_mask:0xf bank_mask:0xf
	v_mov_b32_dpp v26, v61 row_ror:8 row_mask:0xf bank_mask:0xf
	v_mov_b32_dpp v60, v56 row_ror:8 row_mask:0xf bank_mask:0xc
	v_mov_b32_dpp v61, v57 row_ror:8 row_mask:0xf bank_mask:0xc
	v_mov_b32_dpp v56, v25 quad_perm:[0,1,2,3] row_mask:0xf bank_mask:0x3
	v_mov_b32_dpp v57, v26 quad_perm:[0,1,2,3] row_mask:0xf bank_mask:0x3
	v_mov_b32_dpp v25, v62 row_ror:8 row_mask:0xf bank_mask:0xf
	v_mov_b32_dpp v26, v63 row_ror:8 row_mask:0xf bank_mask:0xf
	v_mov_b32_dpp v62, v58 row_ror:8 row_mask:0xf bank_mask:0xc
	v_mov_b32_dpp v63, v59 row_ror:8 row_mask:0xf bank_mask:0xc
	v_mov_b32_dpp v58, v25 quad_perm:[0,1,2,3] row_mask:0xf bank_mask:0x3
	v_mov_b32_dpp v59, v26 quad_perm:[0,1,2,3] row_mask:0xf bank_mask:0x3
	v_mov_b32_dpp v25, v44 row_ror:8 row_mask:0xf bank_mask:0xf
	v_mov_b32_dpp v26, v45 row_ror:8 row_mask:0xf bank_mask:0xf
	v_mov_b32_dpp v44, v40 row_ror:8 row_mask:0xf bank_mask:0xc
	v_mov_b32_dpp v45, v41 row_ror:8 row_mask:0xf bank_mask:0xc
	v_mov_b32_dpp v40, v25 quad_perm:[0,1,2,3] row_mask:0xf bank_mask:0x3
	v_mov_b32_dpp v41, v26 quad_perm:[0,1,2,3] row_mask:0xf bank_mask:0x3
	v_mov_b32_dpp v25, v46 row_ror:8 row_mask:0xf bank_mask:0xf
	v_mov_b32_dpp v26, v47 row_ror:8 row_mask:0xf bank_mask:0xf
	v_mov_b32_dpp v46, v42 row_ror:8 row_mask:0xf bank_mask:0xc
	v_mov_b32_dpp v47, v43 row_ror:8 row_mask:0xf bank_mask:0xc
	v_mov_b32_dpp v42, v25 quad_perm:[0,1,2,3] row_mask:0xf bank_mask:0x3
	v_mov_b32_dpp v43, v26 quad_perm:[0,1,2,3] row_mask:0xf bank_mask:0x3
	v_mov_b32_dpp v25, v36 row_ror:8 row_mask:0xf bank_mask:0xf
	v_mov_b32_dpp v26, v37 row_ror:8 row_mask:0xf bank_mask:0xf
	v_mov_b32_dpp v36, v32 row_ror:8 row_mask:0xf bank_mask:0xc
	v_mov_b32_dpp v37, v33 row_ror:8 row_mask:0xf bank_mask:0xc
	v_mov_b32_dpp v32, v25 quad_perm:[0,1,2,3] row_mask:0xf bank_mask:0x3
	v_mov_b32_dpp v33, v26 quad_perm:[0,1,2,3] row_mask:0xf bank_mask:0x3
; __device__ __forceinline__ unsigned cvt_pk_bf16(float lo, float hi) { unsigned r; asm volatile("v_cvt_pk_bf16_f32 %0, %1, %2" : "=v"(r) : "v"(lo), "v"(hi)); return r; }
;     __device__ __forceinline__ void operator()(const f32x4 (&acc)[2][2][4][2], const Unit& u, int wr, int wc, int fr, int fq, LAS unsigned char* lds) const {
;     ...
;                     const f32x4 r0 = *(const f32x4*)(res + o), r1 = *(const f32x4*)(res + o + 4);
;                     const f32x4 x0 = r0 + acc[ai][bj][m][0], x1 = r1 + acc[ai][bj][m][1];
;                     *(f32x4*)(O + o) = x0; *(f32x4*)(O + o + 4) = x1;
;                     u32x4 hb; hb.x = cvt_pk_bf16(x0[0] * gg[bj][0][0], x0[1] * gg[bj][0][1]); hb.y = cvt_pk_bf16(x0[2] * gg[bj][0][2], x0[3] * gg[bj][0][3]);
;                     hb.z = cvt_pk_bf16(x1[0] * gg[bj][1][0], x1[1] * gg[bj][1][1]); hb.w = cvt_pk_bf16(x1[2] * gg[bj][1][2], x1[3] * gg[bj][1][3]);
;                     *(u32x4*)(H + o) = hb;
;                     ssq += ((x0[0] * x0[0] + x0[1] * x0[1]) + (x0[2] * x0[2] + x0[3] * x0[3])) + ((x1[0] * x1[0] + x1[1] * x1[1]) + (x1[2] * x1[2] + x1[3] * x1[3])); }
;                 ssq += __shfl_xor(ssq, 16); ssq += __shfl_xor(ssq, 32);
;                 if (fq == 0) part[(ai * HALF + wr * 64 + m * 16 + fr) * 4 + wc] = ssq; }
	v_mov_b32_dpp v25, v38 row_ror:8 row_mask:0xf bank_mask:0xf
	v_mov_b32_dpp v26, v39 row_ror:8 row_mask:0xf bank_mask:0xf
	v_mov_b32_dpp v38, v34 row_ror:8 row_mask:0xf bank_mask:0xc
	v_mov_b32_dpp v39, v35 row_ror:8 row_mask:0xf bank_mask:0xc
	v_mov_b32_dpp v34, v25 quad_perm:[0,1,2,3] row_mask:0xf bank_mask:0x3
	v_mov_b32_dpp v35, v26 quad_perm:[0,1,2,3] row_mask:0xf bank_mask:0x3
	v_mov_b32_dpp v25, v20 row_ror:8 row_mask:0xf bank_mask:0xf
	v_mov_b32_dpp v26, v21 row_ror:8 row_mask:0xf bank_mask:0xf
	v_mov_b32_dpp v20, v16 row_ror:8 row_mask:0xf bank_mask:0xc
	v_mov_b32_dpp v21, v17 row_ror:8 row_mask:0xf bank_mask:0xc
	v_mov_b32_dpp v16, v25 quad_perm:[0,1,2,3] row_mask:0xf bank_mask:0x3
	v_mov_b32_dpp v17, v26 quad_perm:[0,1,2,3] row_mask:0xf bank_mask:0x3
	v_mov_b32_dpp v25, v22 row_ror:8 row_mask:0xf bank_mask:0xf
	v_mov_b32_dpp v26, v23 row_ror:8 row_mask:0xf bank_mask:0xf
	v_mov_b32_dpp v22, v18 row_ror:8 row_mask:0xf bank_mask:0xc
	v_mov_b32_dpp v23, v19 row_ror:8 row_mask:0xf bank_mask:0xc
	v_mov_b32_dpp v18, v25 quad_perm:[0,1,2,3] row_mask:0xf bank_mask:0x3
	v_mov_b32_dpp v19, v26 quad_perm:[0,1,2,3] row_mask:0xf bank_mask:0x3
	v_mov_b32_dpp v25, v12 row_ror:8 row_mask:0xf bank_mask:0xf
	v_mov_b32_dpp v26, v13 row_ror:8 row_mask:0xf bank_mask:0xf
	v_mov_b32_dpp v12, v8 row_ror:8 row_mask:0xf bank_mask:0xc
	v_mov_b32_dpp v13, v9 row_ror:8 row_mask:0xf bank_mask:0xc
	v_mov_b32_dpp v8, v25 quad_perm:[0,1,2,3] row_mask:0xf bank_mask:0x3
	v_mov_b32_dpp v9, v26 quad_perm:[0,1,2,3] row_mask:0xf bank_mask:0x3
	v_mov_b32_dpp v25, v14 row_ror:8 row_mask:0xf bank_mask:0xf
	v_mov_b32_dpp v26, v15 row_ror:8 row_mask:0xf bank_mask:0xf
	v_mov_b32_dpp v14, v10 row_ror:8 row_mask:0xf bank_mask:0xc
	v_mov_b32_dpp v15, v11 row_ror:8 row_mask:0xf bank_mask:0xc
	v_mov_b32_dpp v10, v25 quad_perm:[0,1,2,3] row_mask:0xf bank_mask:0x3
	v_mov_b32_dpp v11, v26 quad_perm:[0,1,2,3] row_mask:0xf bank_mask:0x3
	v_mov_b32_dpp v25, v4 row_ror:8 row_mask:0xf bank_mask:0xf
	v_mov_b32_dpp v26, v5 row_ror:8 row_mask:0xf bank_mask:0xf
	v_mov_b32_dpp v4, v0 row_ror:8 row_mask:0xf bank_mask:0xc
	v_mov_b32_dpp v5, v1 row_ror:8 row_mask:0xf bank_mask:0xc
	v_mov_b32_dpp v0, v25 quad_perm:[0,1,2,3] row_mask:0xf bank_mask:0x3
	v_mov_b32_dpp v1, v26 quad_perm:[0,1,2,3] row_mask:0xf bank_mask:0x3
	v_mov_b32_dpp v25, v6 row_ror:8 row_mask:0xf bank_mask:0xf
	v_mov_b32_dpp v26, v7 row_ror:8 row_mask:0xf bank_mask:0xf
	v_mov_b32_dpp v6, v2 row_ror:8 row_mask:0xf bank_mask:0xc
	v_mov_b32_dpp v7, v3 row_ror:8 row_mask:0xf bank_mask:0xc
	v_mov_b32_dpp v2, v25 quad_perm:[0,1,2,3] row_mask:0xf bank_mask:0x3
	v_mov_b32_dpp v3, v26 quad_perm:[0,1,2,3] row_mask:0xf bank_mask:0x3
	s_waitcnt vmcnt(8)
	v_pk_add_f32 v[140:141], v[140:141], v[196:197]
	v_pk_add_f32 v[142:143], v[142:143], v[198:199]
	v_pk_add_f32 v[132:133], v[132:133], v[200:201]
	v_pk_add_f32 v[134:135], v[134:135], v[202:203]
	v_pk_add_f32 v[136:137], v[136:137], v[204:205]
	v_pk_add_f32 v[138:139], v[138:139], v[206:207]
	v_pk_add_f32 v[128:129], v[128:129], v[208:209]
	v_pk_add_f32 v[130:131], v[130:131], v[210:211]
	global_store_dwordx4 v177, v[140:143], s[76:77] nt
	global_store_dwordx4 v177, v[132:135], s[76:77] offset:512 nt
	global_store_dwordx4 v195, v[136:139], s[76:77] nt
	global_store_dwordx4 v195, v[128:131], s[76:77] offset:512 nt
	global_load_dwordx4 v[196:199], v170, s[80:81] nt
	global_load_dwordx4 v[200:203], v170, s[80:81] offset:512 nt
	global_load_dwordx4 v[204:207], v171, s[80:81] nt
	global_load_dwordx4 v[208:211], v171, s[80:81] offset:512 nt
	v_add_u32_e32 v170, 0x50000, v170
	v_add_u32_e32 v171, 0x50000, v171
	v_mul_f32_e32 v27, v180, v140
	v_mul_f32_e32 v28, v181, v141
	v_cvt_pk_bf16_f32 v30, v27, v28
	v_mul_f32_e32 v27, v182, v142
	v_mul_f32_e32 v28, v183, v143
	v_cvt_pk_bf16_f32 v31, v27, v28
	global_store_dwordx2 v247, v[30:31], s[88:89]
	v_mul_f32_e32 v27, v166, v132
	v_mul_f32_e32 v28, v167, v133
	v_cvt_pk_bf16_f32 v48, v27, v28
	v_mul_f32_e32 v27, v168, v134
	v_mul_f32_e32 v28, v169, v135
	v_cvt_pk_bf16_f32 v49, v27, v28
	global_store_dwordx2 v247, v[48:49], s[88:89] offset:256
	v_mul_f32_e32 v27, v180, v136
	v_mul_f32_e32 v28, v181, v137
	v_cvt_pk_bf16_f32 v30, v27, v28
	v_mul_f32_e32 v27, v182, v138
	v_mul_f32_e32 v28, v183, v139
	v_cvt_pk_bf16_f32 v31, v27, v28
	global_store_dwordx2 v24, v[30:31], s[88:89]
	v_mul_f32_e32 v27, v166, v128
	v_mul_f32_e32 v28, v167, v129
	v_cvt_pk_bf16_f32 v48, v27, v28
	v_mul_f32_e32 v27, v168, v130
	v_mul_f32_e32 v28, v169, v131
	v_cvt_pk_bf16_f32 v49, v27, v28
	global_store_dwordx2 v24, v[48:49], s[88:89] offset:256
	v_mul_f32_e32 v50, v141, v141
	v_mul_f32_e32 v29, v143, v143
	v_fmac_f32_e32 v50, v140, v140
	v_fmac_f32_e32 v29, v142, v142
	v_add_f32_e32 v50, v50, v29
	v_mul_f32_e32 v51, v137, v137
	v_mul_f32_e32 v29, v139, v139
	v_fmac_f32_e32 v51, v136, v136
	v_fmac_f32_e32 v29, v138, v138
	v_add_f32_e32 v51, v51, v29
	v_mul_f32_e32 v52, v133, v133
	v_mul_f32_e32 v29, v135, v135
	v_fmac_f32_e32 v52, v132, v132
	v_fmac_f32_e32 v29, v134, v134
	v_add_f32_e32 v52, v52, v29
	v_mul_f32_e32 v53, v129, v129
	v_mul_f32_e32 v29, v131, v131
	v_fmac_f32_e32 v53, v128, v128
	v_fmac_f32_e32 v29, v130, v130
	v_add_f32_e32 v53, v53, v29
	v_add_f32_dpp v27, v50, v50 row_ror:8 row_mask:0xf bank_mask:0x3
	v_add_f32_dpp v28, v52, v52 row_ror:8 row_mask:0xf bank_mask:0x3
	v_add_f32_dpp v27, v51, v51 row_ror:8 row_mask:0xf bank_mask:0xc
	v_add_f32_dpp v28, v53, v53 row_ror:8 row_mask:0xf bank_mask:0xc
	v_add_f32_e32 v27, v27, v28
	ds_bpermute_b32 v29, v54, v27
	s_waitcnt lgkmcnt(0)
	v_add_f32_e32 v27, v27, v29
	ds_bpermute_b32 v29, v55, v27
	s_waitcnt lgkmcnt(0)
; __device__ __forceinline__ unsigned cvt_pk_bf16(float lo, float hi) { unsigned r; asm volatile("v_cvt_pk_bf16_f32 %0, %1, %2" : "=v"(r) : "v"(lo), "v"(hi)); return r; }
;     __device__ __forceinline__ void operator()(const f32x4 (&acc)[2][2][4][2], const Unit& u, int wr, int wc, int fr, int fq, LAS unsigned char* lds) const {
;     ...
;                 for (int bj = 0; bj < 2; ++bj) { const size_t o = ro + bj * HALF;
;                     const f32x4 r0 = *(const f32x4*)(res + o), r1 = *(const f32x4*)(res + o + 4);
;                     const f32x4 x0 = r0 + acc[ai][bj][m][0], x1 = r1 + acc[ai][bj][m][1];
;                     *(f32x4*)(O + o) = x0; *(f32x4*)(O + o + 4) = x1;
;                     u32x4 hb; hb.x = cvt_pk_bf16(x0[0] * gg[bj][0][0], x0[1] * gg[bj][0][1]); hb.y = cvt_pk_bf16(x0[2] * gg[bj][0][2], x0[3] * gg[bj][0][3]);
;                     hb.z = cvt_pk_bf16(x1[0] * gg[bj][1][0], x1[1] * gg[bj][1][1]); hb.w = cvt_pk_bf16(x1[2] * gg[bj][1][2], x1[3] * gg[bj][1][3]);
;                     *(u32x4*)(H + o) = hb;
;                     ssq += ((x0[0] * x0[0] + x0[1] * x0[1]) + (x0[2] * x0[2] + x0[3] * x0[3])) + ((x1[0] * x1[0] + x1[1] * x1[1]) + (x1[2] * x1[2] + x1[3] * x1[3])); }
;                 ssq += __shfl_xor(ssq, 16); ssq += __shfl_xor(ssq, 32);
;                 if (fq == 0) part[(ai * HALF + wr * 64 + m * 16 + fr) * 4 + wc] = ssq; }
	v_add_f32_e32 v27, v27, v29
	s_and_saveexec_b64 s[14:15], s[42:43]
	ds_write_b32 v176, v27
	s_or_b64 exec, exec, s[14:15]
	v_add_u32_e32 v177, 0x10000, v177
	v_add_u32_e32 v195, 0x10000, v195
	v_add_u32_e32 v247, 0x8000, v247
	v_add_u32_e32 v24, 0x8000, v24
	s_waitcnt vmcnt(16)
	v_pk_add_f32 v[124:125], v[124:125], v[212:213]
	v_pk_add_f32 v[126:127], v[126:127], v[214:215]
	v_pk_add_f32 v[116:117], v[116:117], v[216:217]
	v_pk_add_f32 v[118:119], v[118:119], v[218:219]
	v_pk_add_f32 v[120:121], v[120:121], v[220:221]
	v_pk_add_f32 v[122:123], v[122:123], v[222:223]
	v_pk_add_f32 v[112:113], v[112:113], v[224:225]
	v_pk_add_f32 v[114:115], v[114:115], v[226:227]
	global_store_dwordx4 v177, v[124:127], s[76:77] nt
	global_store_dwordx4 v177, v[116:119], s[76:77] offset:512 nt
	global_store_dwordx4 v195, v[120:123], s[76:77] nt
	global_store_dwordx4 v195, v[112:115], s[76:77] offset:512 nt
	global_load_dwordx4 v[212:215], v170, s[80:81] nt
	global_load_dwordx4 v[216:219], v170, s[80:81] offset:512 nt
	global_load_dwordx4 v[220:223], v171, s[80:81] nt
	global_load_dwordx4 v[224:227], v171, s[80:81] offset:512 nt
	v_add_u32_e32 v170, 0x10000, v170
	v_add_u32_e32 v171, 0x10000, v171
	v_mul_f32_e32 v27, v180, v124
	v_mul_f32_e32 v28, v181, v125
	v_cvt_pk_bf16_f32 v30, v27, v28
	v_mul_f32_e32 v27, v182, v126
	v_mul_f32_e32 v28, v183, v127
	v_cvt_pk_bf16_f32 v31, v27, v28
	global_store_dwordx2 v247, v[30:31], s[88:89]
	v_mul_f32_e32 v27, v166, v116
	v_mul_f32_e32 v28, v167, v117
	v_cvt_pk_bf16_f32 v48, v27, v28
	v_mul_f32_e32 v27, v168, v118
	v_mul_f32_e32 v28, v169, v119
	v_cvt_pk_bf16_f32 v49, v27, v28
	global_store_dwordx2 v247, v[48:49], s[88:89] offset:256
	v_mul_f32_e32 v27, v180, v120
	v_mul_f32_e32 v28, v181, v121
	v_cvt_pk_bf16_f32 v30, v27, v28
	v_mul_f32_e32 v27, v182, v122
	v_mul_f32_e32 v28, v183, v123
	v_cvt_pk_bf16_f32 v31, v27, v28
	global_store_dwordx2 v24, v[30:31], s[88:89]
	v_mul_f32_e32 v27, v166, v112
	v_mul_f32_e32 v28, v167, v113
	v_cvt_pk_bf16_f32 v48, v27, v28
	v_mul_f32_e32 v27, v168, v114
	v_mul_f32_e32 v28, v169, v115
	v_cvt_pk_bf16_f32 v49, v27, v28
	global_store_dwordx2 v24, v[48:49], s[88:89] offset:256
	v_mul_f32_e32 v50, v125, v125
	v_mul_f32_e32 v29, v127, v127
	v_fmac_f32_e32 v50, v124, v124
	v_fmac_f32_e32 v29, v126, v126
	v_add_f32_e32 v50, v50, v29
	v_mul_f32_e32 v51, v121, v121
	v_mul_f32_e32 v29, v123, v123
	v_fmac_f32_e32 v51, v120, v120
	v_fmac_f32_e32 v29, v122, v122
	v_add_f32_e32 v51, v51, v29
	v_mul_f32_e32 v52, v117, v117
	v_mul_f32_e32 v29, v119, v119
	v_fmac_f32_e32 v52, v116, v116
	v_fmac_f32_e32 v29, v118, v118
	v_add_f32_e32 v52, v52, v29
	v_mul_f32_e32 v53, v113, v113
	v_mul_f32_e32 v29, v115, v115
	v_fmac_f32_e32 v53, v112, v112
	v_fmac_f32_e32 v29, v114, v114
	v_add_f32_e32 v53, v53, v29
	v_add_f32_dpp v27, v50, v50 row_ror:8 row_mask:0xf bank_mask:0x3
	v_add_f32_dpp v28, v52, v52 row_ror:8 row_mask:0xf bank_mask:0x3
	v_add_f32_dpp v27, v51, v51 row_ror:8 row_mask:0xf bank_mask:0xc
	v_add_f32_dpp v28, v53, v53 row_ror:8 row_mask:0xf bank_mask:0xc
	v_add_f32_e32 v27, v27, v28
	ds_bpermute_b32 v29, v54, v27
	s_waitcnt lgkmcnt(0)
	v_add_f32_e32 v27, v27, v29
	ds_bpermute_b32 v29, v55, v27
	s_waitcnt lgkmcnt(0)
	v_add_f32_e32 v27, v27, v29
	s_and_saveexec_b64 s[14:15], s[42:43]
	ds_write_b32 v176, v27 offset:256
	s_or_b64 exec, exec, s[14:15]
	v_add_u32_e32 v177, 0x10000, v177
	v_add_u32_e32 v195, 0x10000, v195
	v_add_u32_e32 v247, 0x8000, v247
	v_add_u32_e32 v24, 0x8000, v24
	s_waitcnt vmcnt(24)
	v_pk_add_f32 v[108:109], v[108:109], v[228:229]
	v_pk_add_f32 v[110:111], v[110:111], v[230:231]
	v_pk_add_f32 v[100:101], v[100:101], v[232:233]
	v_pk_add_f32 v[102:103], v[102:103], v[234:235]
	v_pk_add_f32 v[104:105], v[104:105], v[236:237]
	v_pk_add_f32 v[106:107], v[106:107], v[238:239]
	v_pk_add_f32 v[96:97], v[96:97], v[240:241]
	v_pk_add_f32 v[98:99], v[98:99], v[242:243]
	global_store_dwordx4 v177, v[108:111], s[76:77] nt
	global_store_dwordx4 v177, v[100:103], s[76:77] offset:512 nt
	global_store_dwordx4 v195, v[104:107], s[76:77] nt
	global_store_dwordx4 v195, v[96:99], s[76:77] offset:512 nt
	global_load_dwordx4 v[228:231], v170, s[80:81] nt
	global_load_dwordx4 v[232:235], v170, s[80:81] offset:512 nt
	global_load_dwordx4 v[236:239], v171, s[80:81] nt
	global_load_dwordx4 v[240:243], v171, s[80:81] offset:512 nt
	v_add_u32_e32 v170, 0x10000, v170
	v_add_u32_e32 v171, 0x10000, v171
	v_mul_f32_e32 v27, v180, v108
	v_mul_f32_e32 v28, v181, v109
	v_cvt_pk_bf16_f32 v30, v27, v28
	v_mul_f32_e32 v27, v182, v110
	v_mul_f32_e32 v28, v183, v111
	v_cvt_pk_bf16_f32 v31, v27, v28
	global_store_dwordx2 v247, v[30:31], s[88:89]
	v_mul_f32_e32 v27, v166, v100
	v_mul_f32_e32 v28, v167, v101
	v_cvt_pk_bf16_f32 v48, v27, v28
	v_mul_f32_e32 v27, v168, v102
	v_mul_f32_e32 v28, v169, v103
	v_cvt_pk_bf16_f32 v49, v27, v28
	global_store_dwordx2 v247, v[48:49], s[88:89] offset:256
	v_mul_f32_e32 v27, v180, v104
	v_mul_f32_e32 v28, v181, v105
	v_cvt_pk_bf16_f32 v30, v27, v28
	v_mul_f32_e32 v27, v182, v106
	v_mul_f32_e32 v28, v183, v107
	v_cvt_pk_bf16_f32 v31, v27, v28
	global_store_dwordx2 v24, v[30:31], s[88:89]
	v_mul_f32_e32 v27, v166, v96
	v_mul_f32_e32 v28, v167, v97
	v_cvt_pk_bf16_f32 v48, v27, v28
	v_mul_f32_e32 v27, v168, v98
	v_mul_f32_e32 v28, v169, v99
	v_cvt_pk_bf16_f32 v49, v27, v28
	global_store_dwordx2 v24, v[48:49], s[88:89] offset:256
	v_mul_f32_e32 v50, v109, v109
	v_mul_f32_e32 v29, v111, v111
	v_fmac_f32_e32 v50, v108, v108
	v_fmac_f32_e32 v29, v110, v110
	v_add_f32_e32 v50, v50, v29
	v_mul_f32_e32 v51, v105, v105
	v_mul_f32_e32 v29, v107, v107
	v_fmac_f32_e32 v51, v104, v104
	v_fmac_f32_e32 v29, v106, v106
	v_add_f32_e32 v51, v51, v29
	v_mul_f32_e32 v52, v101, v101
	v_mul_f32_e32 v29, v103, v103
	v_fmac_f32_e32 v52, v100, v100
	v_fmac_f32_e32 v29, v102, v102
	v_add_f32_e32 v52, v52, v29
	v_mul_f32_e32 v53, v97, v97
	v_mul_f32_e32 v29, v99, v99
	v_fmac_f32_e32 v53, v96, v96
	v_fmac_f32_e32 v29, v98, v98
	v_add_f32_e32 v53, v53, v29
	v_add_f32_dpp v27, v50, v50 row_ror:8 row_mask:0xf bank_mask:0x3
	v_add_f32_dpp v28, v52, v52 row_ror:8 row_mask:0xf bank_mask:0x3
	v_add_f32_dpp v27, v51, v51 row_ror:8 row_mask:0xf bank_mask:0xc
	v_add_f32_dpp v28, v53, v53 row_ror:8 row_mask:0xf bank_mask:0xc
	v_add_f32_e32 v27, v27, v28
	ds_bpermute_b32 v29, v54, v27
	s_waitcnt lgkmcnt(0)
; __device__ __forceinline__ unsigned cvt_pk_bf16(float lo, float hi) { unsigned r; asm volatile("v_cvt_pk_bf16_f32 %0, %1, %2" : "=v"(r) : "v"(lo), "v"(hi)); return r; }
;     __device__ __forceinline__ void operator()(const f32x4 (&acc)[2][2][4][2], const Unit& u, int wr, int wc, int fr, int fq, LAS unsigned char* lds) const {
;     ...
;                 for (int bj = 0; bj < 2; ++bj) { const size_t o = ro + bj * HALF;
;                     const f32x4 r0 = *(const f32x4*)(res + o), r1 = *(const f32x4*)(res + o + 4);
;                     const f32x4 x0 = r0 + acc[ai][bj][m][0], x1 = r1 + acc[ai][bj][m][1];
;                     *(f32x4*)(O + o) = x0; *(f32x4*)(O + o + 4) = x1;
;                     u32x4 hb; hb.x = cvt_pk_bf16(x0[0] * gg[bj][0][0], x0[1] * gg[bj][0][1]); hb.y = cvt_pk_bf16(x0[2] * gg[bj][0][2], x0[3] * gg[bj][0][3]);
;                     hb.z = cvt_pk_bf16(x1[0] * gg[bj][1][0], x1[1] * gg[bj][1][1]); hb.w = cvt_pk_bf16(x1[2] * gg[bj][1][2], x1[3] * gg[bj][1][3]);
;                     *(u32x4*)(H + o) = hb;
;                     ssq += ((x0[0] * x0[0] + x0[1] * x0[1]) + (x0[2] * x0[2] + x0[3] * x0[3])) + ((x1[0] * x1[0] + x1[1] * x1[1]) + (x1[2] * x1[2] + x1[3] * x1[3])); }
;                 ssq += __shfl_xor(ssq, 16); ssq += __shfl_xor(ssq, 32);
;                 if (fq == 0) part[(ai * HALF + wr * 64 + m * 16 + fr) * 4 + wc] = ssq; }
	v_add_f32_e32 v27, v27, v29
	ds_bpermute_b32 v29, v55, v27
	s_waitcnt lgkmcnt(0)
	v_add_f32_e32 v27, v27, v29
	s_and_saveexec_b64 s[14:15], s[42:43]
	ds_write_b32 v176, v27 offset:512
	s_or_b64 exec, exec, s[14:15]
	v_add_u32_e32 v177, 0x10000, v177
	v_add_u32_e32 v195, 0x10000, v195
	v_add_u32_e32 v247, 0x8000, v247
	v_add_u32_e32 v24, 0x8000, v24
	s_waitcnt vmcnt(28)
	v_pk_add_f32 v[92:93], v[92:93], v[196:197]
	v_pk_add_f32 v[94:95], v[94:95], v[198:199]
	v_pk_add_f32 v[84:85], v[84:85], v[200:201]
	v_pk_add_f32 v[86:87], v[86:87], v[202:203]
	v_pk_add_f32 v[88:89], v[88:89], v[204:205]
	v_pk_add_f32 v[90:91], v[90:91], v[206:207]
	v_pk_add_f32 v[80:81], v[80:81], v[208:209]
	v_pk_add_f32 v[82:83], v[82:83], v[210:211]
	global_store_dwordx4 v177, v[92:95], s[76:77] nt
	global_store_dwordx4 v177, v[84:87], s[76:77] offset:512 nt
	global_store_dwordx4 v195, v[88:91], s[76:77] nt
	global_store_dwordx4 v195, v[80:83], s[76:77] offset:512 nt
	global_load_dwordx4 v[196:199], v170, s[80:81] nt
	global_load_dwordx4 v[200:203], v170, s[80:81] offset:512 nt
	global_load_dwordx4 v[204:207], v171, s[80:81] nt
	global_load_dwordx4 v[208:211], v171, s[80:81] offset:512 nt
	v_add_u32_e32 v170, 0x10000, v170
	v_add_u32_e32 v171, 0x10000, v171
	v_mul_f32_e32 v27, v180, v92
	v_mul_f32_e32 v28, v181, v93
	v_cvt_pk_bf16_f32 v30, v27, v28
	v_mul_f32_e32 v27, v182, v94
	v_mul_f32_e32 v28, v183, v95
	v_cvt_pk_bf16_f32 v31, v27, v28
	global_store_dwordx2 v247, v[30:31], s[88:89]
	v_mul_f32_e32 v27, v166, v84
	v_mul_f32_e32 v28, v167, v85
	v_cvt_pk_bf16_f32 v48, v27, v28
	v_mul_f32_e32 v27, v168, v86
	v_mul_f32_e32 v28, v169, v87
	v_cvt_pk_bf16_f32 v49, v27, v28
	global_store_dwordx2 v247, v[48:49], s[88:89] offset:256
	v_mul_f32_e32 v27, v180, v88
	v_mul_f32_e32 v28, v181, v89
	v_cvt_pk_bf16_f32 v30, v27, v28
	v_mul_f32_e32 v27, v182, v90
	v_mul_f32_e32 v28, v183, v91
	v_cvt_pk_bf16_f32 v31, v27, v28
	global_store_dwordx2 v24, v[30:31], s[88:89]
	v_mul_f32_e32 v27, v166, v80
	v_mul_f32_e32 v28, v167, v81
	v_cvt_pk_bf16_f32 v48, v27, v28
	v_mul_f32_e32 v27, v168, v82
	v_mul_f32_e32 v28, v169, v83
	v_cvt_pk_bf16_f32 v49, v27, v28
	global_store_dwordx2 v24, v[48:49], s[88:89] offset:256
	v_mul_f32_e32 v50, v93, v93
	v_mul_f32_e32 v29, v95, v95
	v_fmac_f32_e32 v50, v92, v92
	v_fmac_f32_e32 v29, v94, v94
	v_add_f32_e32 v50, v50, v29
	v_mul_f32_e32 v51, v89, v89
	v_mul_f32_e32 v29, v91, v91
	v_fmac_f32_e32 v51, v88, v88
	v_fmac_f32_e32 v29, v90, v90
	v_add_f32_e32 v51, v51, v29
	v_mul_f32_e32 v52, v85, v85
	v_mul_f32_e32 v29, v87, v87
	v_fmac_f32_e32 v52, v84, v84
	v_fmac_f32_e32 v29, v86, v86
	v_add_f32_e32 v52, v52, v29
	v_mul_f32_e32 v53, v81, v81
	v_mul_f32_e32 v29, v83, v83
	v_fmac_f32_e32 v53, v80, v80
	v_fmac_f32_e32 v29, v82, v82
	v_add_f32_e32 v53, v53, v29
	v_add_f32_dpp v27, v50, v50 row_ror:8 row_mask:0xf bank_mask:0x3
	v_add_f32_dpp v28, v52, v52 row_ror:8 row_mask:0xf bank_mask:0x3
	v_add_f32_dpp v27, v51, v51 row_ror:8 row_mask:0xf bank_mask:0xc
	v_add_f32_dpp v28, v53, v53 row_ror:8 row_mask:0xf bank_mask:0xc
	v_add_f32_e32 v27, v27, v28
	ds_bpermute_b32 v29, v54, v27
	s_waitcnt lgkmcnt(0)
	v_add_f32_e32 v27, v27, v29
	ds_bpermute_b32 v29, v55, v27
	s_waitcnt lgkmcnt(0)
	v_add_f32_e32 v27, v27, v29
	s_and_saveexec_b64 s[14:15], s[42:43]
	ds_write_b32 v176, v27 offset:768
	s_or_b64 exec, exec, s[14:15]
	v_add_u32_e32 v177, 0x50000, v177
	v_add_u32_e32 v195, 0x50000, v195
	v_add_u32_e32 v247, 0x28000, v247
	v_add_u32_e32 v24, 0x28000, v24
	s_waitcnt vmcnt(28)
	v_pk_add_f32 v[76:77], v[76:77], v[212:213]
	v_pk_add_f32 v[78:79], v[78:79], v[214:215]
	v_pk_add_f32 v[68:69], v[68:69], v[216:217]
	v_pk_add_f32 v[70:71], v[70:71], v[218:219]
	v_pk_add_f32 v[72:73], v[72:73], v[220:221]
	v_pk_add_f32 v[74:75], v[74:75], v[222:223]
	v_pk_add_f32 v[64:65], v[64:65], v[224:225]
	v_pk_add_f32 v[66:67], v[66:67], v[226:227]
	global_store_dwordx4 v177, v[76:79], s[76:77] nt
	global_store_dwordx4 v177, v[68:71], s[76:77] offset:512 nt
	global_store_dwordx4 v195, v[72:75], s[76:77] nt
	global_store_dwordx4 v195, v[64:67], s[76:77] offset:512 nt
	global_load_dwordx4 v[212:215], v170, s[80:81] nt
	global_load_dwordx4 v[216:219], v170, s[80:81] offset:512 nt
	global_load_dwordx4 v[220:223], v171, s[80:81] nt
	global_load_dwordx4 v[224:227], v171, s[80:81] offset:512 nt
	v_mul_f32_e32 v27, v180, v76
	v_mul_f32_e32 v28, v181, v77
	v_cvt_pk_bf16_f32 v30, v27, v28
	v_mul_f32_e32 v27, v182, v78
	v_mul_f32_e32 v28, v183, v79
	v_cvt_pk_bf16_f32 v31, v27, v28
	global_store_dwordx2 v247, v[30:31], s[88:89]
	v_mul_f32_e32 v27, v166, v68
	v_mul_f32_e32 v28, v167, v69
	v_cvt_pk_bf16_f32 v48, v27, v28
	v_mul_f32_e32 v27, v168, v70
	v_mul_f32_e32 v28, v169, v71
	v_cvt_pk_bf16_f32 v49, v27, v28
	global_store_dwordx2 v247, v[48:49], s[88:89] offset:256
	v_mul_f32_e32 v27, v180, v72
	v_mul_f32_e32 v28, v181, v73
	v_cvt_pk_bf16_f32 v30, v27, v28
	v_mul_f32_e32 v27, v182, v74
	v_mul_f32_e32 v28, v183, v75
	v_cvt_pk_bf16_f32 v31, v27, v28
	global_store_dwordx2 v24, v[30:31], s[88:89]
	v_mul_f32_e32 v27, v166, v64
	v_mul_f32_e32 v28, v167, v65
	v_cvt_pk_bf16_f32 v48, v27, v28
	v_mul_f32_e32 v27, v168, v66
	v_mul_f32_e32 v28, v169, v67
	v_cvt_pk_bf16_f32 v49, v27, v28
	global_store_dwordx2 v24, v[48:49], s[88:89] offset:256
	v_mul_f32_e32 v50, v77, v77
	v_mul_f32_e32 v29, v79, v79
	v_fmac_f32_e32 v50, v76, v76
	v_fmac_f32_e32 v29, v78, v78
	v_add_f32_e32 v50, v50, v29
	v_mul_f32_e32 v51, v73, v73
	v_mul_f32_e32 v29, v75, v75
	v_fmac_f32_e32 v51, v72, v72
	v_fmac_f32_e32 v29, v74, v74
	v_add_f32_e32 v51, v51, v29
	v_mul_f32_e32 v52, v69, v69
	v_mul_f32_e32 v29, v71, v71
	v_fmac_f32_e32 v52, v68, v68
	v_fmac_f32_e32 v29, v70, v70
	v_add_f32_e32 v52, v52, v29
	v_mul_f32_e32 v53, v65, v65
	v_mul_f32_e32 v29, v67, v67
	v_fmac_f32_e32 v53, v64, v64
	v_fmac_f32_e32 v29, v66, v66
	v_add_f32_e32 v53, v53, v29
	v_add_f32_dpp v27, v50, v50 row_ror:8 row_mask:0xf bank_mask:0x3
	v_add_f32_dpp v28, v52, v52 row_ror:8 row_mask:0xf bank_mask:0x3
	v_add_f32_dpp v27, v51, v51 row_ror:8 row_mask:0xf bank_mask:0xc
	v_add_f32_dpp v28, v53, v53 row_ror:8 row_mask:0xf bank_mask:0xc
	v_add_f32_e32 v27, v27, v28
	ds_bpermute_b32 v29, v54, v27
	s_waitcnt lgkmcnt(0)
; __device__ __forceinline__ unsigned cvt_pk_bf16(float lo, float hi) { unsigned r; asm volatile("v_cvt_pk_bf16_f32 %0, %1, %2" : "=v"(r) : "v"(lo), "v"(hi)); return r; }
;     __device__ __forceinline__ void operator()(const f32x4 (&acc)[2][2][4][2], const Unit& u, int wr, int wc, int fr, int fq, LAS unsigned char* lds) const {
;     ...
;                 for (int bj = 0; bj < 2; ++bj) { const size_t o = ro + bj * HALF;
;                     const f32x4 r0 = *(const f32x4*)(res + o), r1 = *(const f32x4*)(res + o + 4);
;                     const f32x4 x0 = r0 + acc[ai][bj][m][0], x1 = r1 + acc[ai][bj][m][1];
;                     *(f32x4*)(O + o) = x0; *(f32x4*)(O + o + 4) = x1;
;                     u32x4 hb; hb.x = cvt_pk_bf16(x0[0] * gg[bj][0][0], x0[1] * gg[bj][0][1]); hb.y = cvt_pk_bf16(x0[2] * gg[bj][0][2], x0[3] * gg[bj][0][3]);
;                     hb.z = cvt_pk_bf16(x1[0] * gg[bj][1][0], x1[1] * gg[bj][1][1]); hb.w = cvt_pk_bf16(x1[2] * gg[bj][1][2], x1[3] * gg[bj][1][3]);
;                     *(u32x4*)(H + o) = hb;
;                     ssq += ((x0[0] * x0[0] + x0[1] * x0[1]) + (x0[2] * x0[2] + x0[3] * x0[3])) + ((x1[0] * x1[0] + x1[1] * x1[1]) + (x1[2] * x1[2] + x1[3] * x1[3])); }
;                 ssq += __shfl_xor(ssq, 16); ssq += __shfl_xor(ssq, 32);
;                 if (fq == 0) part[(ai * HALF + wr * 64 + m * 16 + fr) * 4 + wc] = ssq; }
	v_add_f32_e32 v27, v27, v29
	ds_bpermute_b32 v29, v55, v27
	s_waitcnt lgkmcnt(0)
	v_add_f32_e32 v27, v27, v29
	s_and_saveexec_b64 s[14:15], s[42:43]
	ds_write_b32 v176, v27 offset:2048
	s_or_b64 exec, exec, s[14:15]
	v_add_u32_e32 v177, 0x10000, v177
	v_add_u32_e32 v195, 0x10000, v195
	v_add_u32_e32 v247, 0x8000, v247
	v_add_u32_e32 v24, 0x8000, v24
	s_waitcnt vmcnt(28)
	v_pk_add_f32 v[60:61], v[60:61], v[228:229]
	v_pk_add_f32 v[62:63], v[62:63], v[230:231]
	v_pk_add_f32 v[44:45], v[44:45], v[232:233]
	v_pk_add_f32 v[46:47], v[46:47], v[234:235]
	v_pk_add_f32 v[56:57], v[56:57], v[236:237]
	v_pk_add_f32 v[58:59], v[58:59], v[238:239]
	v_pk_add_f32 v[40:41], v[40:41], v[240:241]
	v_pk_add_f32 v[42:43], v[42:43], v[242:243]
	global_store_dwordx4 v177, v[60:63], s[76:77] nt
	global_store_dwordx4 v177, v[44:47], s[76:77] offset:512 nt
	global_store_dwordx4 v195, v[56:59], s[76:77] nt
	global_store_dwordx4 v195, v[40:43], s[76:77] offset:512 nt
	v_mul_f32_e32 v27, v180, v60
	v_mul_f32_e32 v28, v181, v61
	v_cvt_pk_bf16_f32 v30, v27, v28
	v_mul_f32_e32 v27, v182, v62
	v_mul_f32_e32 v28, v183, v63
	v_cvt_pk_bf16_f32 v31, v27, v28
	global_store_dwordx2 v247, v[30:31], s[88:89]
	v_mul_f32_e32 v27, v166, v44
	v_mul_f32_e32 v28, v167, v45
	v_cvt_pk_bf16_f32 v48, v27, v28
	v_mul_f32_e32 v27, v168, v46
	v_mul_f32_e32 v28, v169, v47
	v_cvt_pk_bf16_f32 v49, v27, v28
	global_store_dwordx2 v247, v[48:49], s[88:89] offset:256
	v_mul_f32_e32 v27, v180, v56
	v_mul_f32_e32 v28, v181, v57
	v_cvt_pk_bf16_f32 v30, v27, v28
	v_mul_f32_e32 v27, v182, v58
	v_mul_f32_e32 v28, v183, v59
	v_cvt_pk_bf16_f32 v31, v27, v28
	global_store_dwordx2 v24, v[30:31], s[88:89]
	v_mul_f32_e32 v27, v166, v40
	v_mul_f32_e32 v28, v167, v41
	v_cvt_pk_bf16_f32 v48, v27, v28
	v_mul_f32_e32 v27, v168, v42
	v_mul_f32_e32 v28, v169, v43
	v_cvt_pk_bf16_f32 v49, v27, v28
	global_store_dwordx2 v24, v[48:49], s[88:89] offset:256
	v_mul_f32_e32 v50, v61, v61
	v_mul_f32_e32 v29, v63, v63
	v_fmac_f32_e32 v50, v60, v60
	v_fmac_f32_e32 v29, v62, v62
	v_add_f32_e32 v50, v50, v29
	v_mul_f32_e32 v51, v57, v57
	v_mul_f32_e32 v29, v59, v59
	v_fmac_f32_e32 v51, v56, v56
	v_fmac_f32_e32 v29, v58, v58
	v_add_f32_e32 v51, v51, v29
	v_mul_f32_e32 v52, v45, v45
	v_mul_f32_e32 v29, v47, v47
	v_fmac_f32_e32 v52, v44, v44
	v_fmac_f32_e32 v29, v46, v46
	v_add_f32_e32 v52, v52, v29
	v_mul_f32_e32 v53, v41, v41
	v_mul_f32_e32 v29, v43, v43
	v_fmac_f32_e32 v53, v40, v40
	v_fmac_f32_e32 v29, v42, v42
	v_add_f32_e32 v53, v53, v29
	v_add_f32_dpp v27, v50, v50 row_ror:8 row_mask:0xf bank_mask:0x3
	v_add_f32_dpp v28, v52, v52 row_ror:8 row_mask:0xf bank_mask:0x3
	v_add_f32_dpp v27, v51, v51 row_ror:8 row_mask:0xf bank_mask:0xc
	v_add_f32_dpp v28, v53, v53 row_ror:8 row_mask:0xf bank_mask:0xc
	v_add_f32_e32 v27, v27, v28
	ds_bpermute_b32 v29, v54, v27
	s_waitcnt lgkmcnt(0)
	v_add_f32_e32 v27, v27, v29
	ds_bpermute_b32 v29, v55, v27
	s_waitcnt lgkmcnt(0)
	v_add_f32_e32 v27, v27, v29
	s_and_saveexec_b64 s[14:15], s[42:43]
	ds_write_b32 v176, v27 offset:2304
	s_or_b64 exec, exec, s[14:15]
	v_add_u32_e32 v177, 0x10000, v177
	v_add_u32_e32 v195, 0x10000, v195
	v_add_u32_e32 v247, 0x8000, v247
	v_add_u32_e32 v24, 0x8000, v24
	s_waitcnt vmcnt(24)
	v_pk_add_f32 v[36:37], v[36:37], v[196:197]
	v_pk_add_f32 v[38:39], v[38:39], v[198:199]
	v_pk_add_f32 v[20:21], v[20:21], v[200:201]
	v_pk_add_f32 v[22:23], v[22:23], v[202:203]
	v_pk_add_f32 v[32:33], v[32:33], v[204:205]
	v_pk_add_f32 v[34:35], v[34:35], v[206:207]
	v_pk_add_f32 v[16:17], v[16:17], v[208:209]
	v_pk_add_f32 v[18:19], v[18:19], v[210:211]
	global_store_dwordx4 v177, v[36:39], s[76:77] nt
	global_store_dwordx4 v177, v[20:23], s[76:77] offset:512 nt
	global_store_dwordx4 v195, v[32:35], s[76:77] nt
	global_store_dwordx4 v195, v[16:19], s[76:77] offset:512 nt
	v_mul_f32_e32 v27, v180, v36
	v_mul_f32_e32 v28, v181, v37
	v_cvt_pk_bf16_f32 v30, v27, v28
	v_mul_f32_e32 v27, v182, v38
	v_mul_f32_e32 v28, v183, v39
	v_cvt_pk_bf16_f32 v31, v27, v28
	global_store_dwordx2 v247, v[30:31], s[88:89]
	v_mul_f32_e32 v27, v166, v20
	v_mul_f32_e32 v28, v167, v21
	v_cvt_pk_bf16_f32 v48, v27, v28
	v_mul_f32_e32 v27, v168, v22
	v_mul_f32_e32 v28, v169, v23
	v_cvt_pk_bf16_f32 v49, v27, v28
	global_store_dwordx2 v247, v[48:49], s[88:89] offset:256
	v_mul_f32_e32 v27, v180, v32
	v_mul_f32_e32 v28, v181, v33
	v_cvt_pk_bf16_f32 v30, v27, v28
	v_mul_f32_e32 v27, v182, v34
	v_mul_f32_e32 v28, v183, v35
	v_cvt_pk_bf16_f32 v31, v27, v28
	global_store_dwordx2 v24, v[30:31], s[88:89]
	v_mul_f32_e32 v27, v166, v16
	v_mul_f32_e32 v28, v167, v17
	v_cvt_pk_bf16_f32 v48, v27, v28
	v_mul_f32_e32 v27, v168, v18
	v_mul_f32_e32 v28, v169, v19
	v_cvt_pk_bf16_f32 v49, v27, v28
	global_store_dwordx2 v24, v[48:49], s[88:89] offset:256
	v_mul_f32_e32 v50, v37, v37
	v_mul_f32_e32 v29, v39, v39
	v_fmac_f32_e32 v50, v36, v36
	v_fmac_f32_e32 v29, v38, v38
	v_add_f32_e32 v50, v50, v29
	v_mul_f32_e32 v51, v33, v33
	v_mul_f32_e32 v29, v35, v35
	v_fmac_f32_e32 v51, v32, v32
	v_fmac_f32_e32 v29, v34, v34
	v_add_f32_e32 v51, v51, v29
	v_mul_f32_e32 v52, v21, v21
	v_mul_f32_e32 v29, v23, v23
	v_fmac_f32_e32 v52, v20, v20
	v_fmac_f32_e32 v29, v22, v22
	v_add_f32_e32 v52, v52, v29
	v_mul_f32_e32 v53, v17, v17
	v_mul_f32_e32 v29, v19, v19
	v_fmac_f32_e32 v53, v16, v16
	v_fmac_f32_e32 v29, v18, v18
	v_add_f32_e32 v53, v53, v29
	v_add_f32_dpp v27, v50, v50 row_ror:8 row_mask:0xf bank_mask:0x3
	v_add_f32_dpp v28, v52, v52 row_ror:8 row_mask:0xf bank_mask:0x3
	v_add_f32_dpp v27, v51, v51 row_ror:8 row_mask:0xf bank_mask:0xc
	v_add_f32_dpp v28, v53, v53 row_ror:8 row_mask:0xf bank_mask:0xc
	v_add_f32_e32 v27, v27, v28
	ds_bpermute_b32 v29, v54, v27
	s_waitcnt lgkmcnt(0)
; #define LAS __attribute__((address_space(3)))
; __device__ __forceinline__ unsigned cvt_pk_bf16(float lo, float hi) { unsigned r; asm volatile("v_cvt_pk_bf16_f32 %0, %1, %2" : "=v"(r) : "v"(lo), "v"(hi)); return r; }
;     __device__ __forceinline__ void operator()(const f32x4 (&acc)[2][2][4][2], const Unit& u, int wr, int wc, int fr, int fq, LAS unsigned char* lds) const {
;     ...
;                 for (int bj = 0; bj < 2; ++bj) { const size_t o = ro + bj * HALF;
;                     const f32x4 r0 = *(const f32x4*)(res + o), r1 = *(const f32x4*)(res + o + 4);
;                     const f32x4 x0 = r0 + acc[ai][bj][m][0], x1 = r1 + acc[ai][bj][m][1];
;                     *(f32x4*)(O + o) = x0; *(f32x4*)(O + o + 4) = x1;
;                     u32x4 hb; hb.x = cvt_pk_bf16(x0[0] * gg[bj][0][0], x0[1] * gg[bj][0][1]); hb.y = cvt_pk_bf16(x0[2] * gg[bj][0][2], x0[3] * gg[bj][0][3]);
;                     hb.z = cvt_pk_bf16(x1[0] * gg[bj][1][0], x1[1] * gg[bj][1][1]); hb.w = cvt_pk_bf16(x1[2] * gg[bj][1][2], x1[3] * gg[bj][1][3]);
;                     *(u32x4*)(H + o) = hb;
;                     ssq += ((x0[0] * x0[0] + x0[1] * x0[1]) + (x0[2] * x0[2] + x0[3] * x0[3])) + ((x1[0] * x1[0] + x1[1] * x1[1]) + (x1[2] * x1[2] + x1[3] * x1[3])); }
;                 ssq += __shfl_xor(ssq, 16); ssq += __shfl_xor(ssq, 32);
;                 if (fq == 0) part[(ai * HALF + wr * 64 + m * 16 + fr) * 4 + wc] = ssq; }
;         asm volatile("s_waitcnt lgkmcnt(0)" ::: "memory"); __builtin_amdgcn_s_barrier(); asm volatile("" ::: "memory");
;         const int t = threadIdx.x;
;         if (t < 256) { const f32x4 p = *(const LAS f32x4*)(part + t * 4); rss[(size_t)u.pn * NTOK + u.pm * BM + t] = (p[0] + p[1]) + (p[2] + p[3]); }
	v_add_f32_e32 v27, v27, v29
	ds_bpermute_b32 v29, v55, v27
	s_waitcnt lgkmcnt(0)
	v_add_f32_e32 v27, v27, v29
	s_and_saveexec_b64 s[14:15], s[42:43]
	ds_write_b32 v176, v27 offset:2560
	s_or_b64 exec, exec, s[14:15]
	v_add_u32_e32 v177, 0x10000, v177
	v_add_u32_e32 v195, 0x10000, v195
	v_add_u32_e32 v247, 0x8000, v247
	v_add_u32_e32 v24, 0x8000, v24
	s_waitcnt vmcnt(20)
	v_pk_add_f32 v[12:13], v[12:13], v[212:213]
	v_pk_add_f32 v[14:15], v[14:15], v[214:215]
	v_pk_add_f32 v[4:5], v[4:5], v[216:217]
	v_pk_add_f32 v[6:7], v[6:7], v[218:219]
	v_pk_add_f32 v[8:9], v[8:9], v[220:221]
	v_pk_add_f32 v[10:11], v[10:11], v[222:223]
	v_pk_add_f32 v[0:1], v[0:1], v[224:225]
	v_pk_add_f32 v[2:3], v[2:3], v[226:227]
	global_store_dwordx4 v177, v[12:15], s[76:77] nt
	global_store_dwordx4 v177, v[4:7], s[76:77] offset:512 nt
	global_store_dwordx4 v195, v[8:11], s[76:77] nt
	global_store_dwordx4 v195, v[0:3], s[76:77] offset:512 nt
	v_mul_f32_e32 v27, v180, v12
	v_mul_f32_e32 v28, v181, v13
	v_cvt_pk_bf16_f32 v30, v27, v28
	v_mul_f32_e32 v27, v182, v14
	v_mul_f32_e32 v28, v183, v15
	v_cvt_pk_bf16_f32 v31, v27, v28
	global_store_dwordx2 v247, v[30:31], s[88:89]
	v_mul_f32_e32 v27, v166, v4
	v_mul_f32_e32 v28, v167, v5
	v_cvt_pk_bf16_f32 v48, v27, v28
	v_mul_f32_e32 v27, v168, v6
	v_mul_f32_e32 v28, v169, v7
	v_cvt_pk_bf16_f32 v49, v27, v28
	global_store_dwordx2 v247, v[48:49], s[88:89] offset:256
	v_mul_f32_e32 v27, v180, v8
	v_mul_f32_e32 v28, v181, v9
	v_cvt_pk_bf16_f32 v30, v27, v28
	v_mul_f32_e32 v27, v182, v10
	v_mul_f32_e32 v28, v183, v11
	v_cvt_pk_bf16_f32 v31, v27, v28
	global_store_dwordx2 v24, v[30:31], s[88:89]
	v_mul_f32_e32 v27, v166, v0
	v_mul_f32_e32 v28, v167, v1
	v_cvt_pk_bf16_f32 v48, v27, v28
	v_mul_f32_e32 v27, v168, v2
	v_mul_f32_e32 v28, v169, v3
	v_cvt_pk_bf16_f32 v49, v27, v28
	global_store_dwordx2 v24, v[48:49], s[88:89] offset:256
	v_mul_f32_e32 v50, v13, v13
	v_mul_f32_e32 v29, v15, v15
	v_fmac_f32_e32 v50, v12, v12
	v_fmac_f32_e32 v29, v14, v14
	v_add_f32_e32 v50, v50, v29
	v_mul_f32_e32 v51, v9, v9
	v_mul_f32_e32 v29, v11, v11
	v_fmac_f32_e32 v51, v8, v8
	v_fmac_f32_e32 v29, v10, v10
	v_add_f32_e32 v51, v51, v29
	v_mul_f32_e32 v52, v5, v5
	v_mul_f32_e32 v29, v7, v7
	v_fmac_f32_e32 v52, v4, v4
	v_fmac_f32_e32 v29, v6, v6
	v_add_f32_e32 v52, v52, v29
	v_mul_f32_e32 v53, v1, v1
	v_mul_f32_e32 v29, v3, v3
	v_fmac_f32_e32 v53, v0, v0
	v_fmac_f32_e32 v29, v2, v2
	v_add_f32_e32 v53, v53, v29
	v_add_f32_dpp v27, v50, v50 row_ror:8 row_mask:0xf bank_mask:0x3
	v_add_f32_dpp v28, v52, v52 row_ror:8 row_mask:0xf bank_mask:0x3
	v_add_f32_dpp v27, v51, v51 row_ror:8 row_mask:0xf bank_mask:0xc
	v_add_f32_dpp v28, v53, v53 row_ror:8 row_mask:0xf bank_mask:0xc
	v_add_f32_e32 v27, v27, v28
	ds_bpermute_b32 v29, v54, v27
	s_waitcnt lgkmcnt(0)
	v_add_f32_e32 v27, v27, v29
	ds_bpermute_b32 v29, v55, v27
	s_waitcnt lgkmcnt(0)
	v_add_f32_e32 v27, v27, v29
	s_and_saveexec_b64 s[14:15], s[42:43]
	ds_write_b32 v176, v27 offset:2816
	s_or_b64 exec, exec, s[14:15]
	s_waitcnt lgkmcnt(0)
	s_barrier
	s_mov_b64 s[14:15], exec
	v_readlane_b32 s4, v246, 6
	v_readlane_b32 s5, v246, 7
	s_and_b64 s[4:5], s[14:15], s[4:5]
	s_mov_b64 exec, s[4:5]
	s_cbranch_execz .LBB0_804
	s_waitcnt lgkmcnt(0)
	ds_read_b128 v[0:3], v189
	s_ashr_i32 s57, s56, 31
	s_ashr_i32 s47, s46, 31
	s_lshl_b64 s[4:5], s[56:57], 16
	v_readlane_b32 s16, v246, 4
	v_readlane_b32 s17, v246, 5
	s_add_u32 s16, s16, s4
	s_addc_u32 s17, s17, s5
	s_lshl_b64 s[4:5], s[46:47], 2
	s_waitcnt lgkmcnt(0)
	v_mov_b32_e32 v4, v1
	v_mov_b32_e32 v5, v2
	v_mov_b32_e32 v1, v3
	s_add_u32 s4, s16, s4
	v_pk_add_f32 v[0:1], v[4:5], v[0:1]
	s_addc_u32 s5, s17, s5
	v_add_f32_e32 v2, v0, v1
	v_lshl_add_u64 v[0:1], v[178:179], 2, s[4:5]
	global_store_dword v[0:1], v2, off
